# added: SSD chunk-loop counted waits no longer blocked by the previous chunk's Y stores; SSD finalize norm-gain loads hoisted out of the row loop
# baseline (speedup 1.0000x reference)
; __global__ void __launch_bounds__(512, 2) hybrid_fwd(Params P0) {
;     ...
;         } else if (sub == 4 && PHON(4)) {
;             const bf16_t* YF = (const bf16_t*)(P.ws + WS_YF); const bf16_t* YB = (const bf16_t*)(P.ws + WS_YB); const bf16_t* xbc = (const bf16_t*)(P.ws + WS_XBC);
;             const bf16_t* proj = (const bf16_t*)(P.ws + WS_PROJ); bf16_t* mix = (bf16_t*)(P.ws + WS_MIX);
;             for (int m2 = gw; m2 < T / 2; m2 += NGW) { const int m = 2 * m2;
;                 float y[24]; float ss0 = 0.f, ss1 = 0.f;
; #pragma unroll
;                 for (int j = 0; j < 3; ++j) { const int f = (j * 64 + lane) * 8, rw = f >= SSD_W ? 1 : 0, c0 = f - rw * SSD_W; const size_t row = (size_t)(m + rw);
;                     const u32x4 a = *(const u32x4*)(YF + row * SSD_W + c0), b = *(const u32x4*)(YB + row * SSD_W + c0), x = *(const u32x4*)(xbc + row * XBC_W + c0), z = *(const u32x4*)(proj + row * PROJ_PITCH + ZOFF + c0);
;                     const float dsk = P.in[I_SSDD][L * 12 + c0 / 64];
;                     float fa[8], fb[8], fx[8], fz[8]; unpack8(a, fa); unpack8(b, fb); unpack8(x, fx); unpack8(z, fz); float sq = 0.f;
.LBB0_38:
	s_cmpk_gt_i32 s68, 0x4fff
	s_cbranch_scc1 .LBB0_41
	v_and_b32_e32 v1, 64, v227
	v_add_u32_e32 v1, 64, v1
	v_xor_b32_e32 v2, 1, v227
	v_cmp_lt_i32_e32 vcc, v2, v1
	s_add_u32 s8, s26, 0x38e00000
	s_load_dwordx4 s[4:7], s[64:65], 0x70
	v_cndmask_b32_e32 v2, v227, v2, vcc
	v_lshlrev_b32_e32 v95, 2, v2
	v_xor_b32_e32 v2, 2, v227
	v_cmp_lt_i32_e32 vcc, v2, v1
	s_addc_u32 s9, s27, 0
	s_add_u32 s10, s26, 0xaa00000
	v_cndmask_b32_e32 v2, v227, v2, vcc
	v_lshlrev_b32_e32 v97, 2, v2
	v_xor_b32_e32 v2, 4, v227
	v_cmp_lt_i32_e32 vcc, v2, v1
	s_mul_i32 s0, s28, 0x300
	s_addc_u32 s11, s27, 0
	v_cndmask_b32_e32 v2, v227, v2, vcc
	v_lshlrev_b32_e32 v100, 2, v2
	v_xor_b32_e32 v2, 8, v227
	v_cmp_lt_i32_e32 vcc, v2, v1
	s_mul_i32 s2, s28, 12
	s_ashr_i32 s1, s0, 31
	v_cndmask_b32_e32 v2, v227, v2, vcc
	v_lshlrev_b32_e32 v101, 2, v2
	v_xor_b32_e32 v2, 16, v227
	v_cmp_lt_i32_e32 vcc, v2, v1
	v_lshlrev_b32_e32 v0, 3, v198
	s_lshl_b64 s[0:1], s[0:1], 2
	v_cndmask_b32_e32 v2, v227, v2, vcc
	v_lshlrev_b32_e32 v102, 2, v2
	v_xor_b32_e32 v2, 32, v227
	v_cmp_lt_i32_e32 vcc, v2, v1
	s_waitcnt lgkmcnt(0)
	s_add_u32 s6, s6, s0
	s_movk_i32 s0, 0x2ff
	v_cndmask_b32_e32 v1, v227, v2, vcc
	v_lshrrev_b32_e32 v2, 3, v198
	v_add_u32_e32 v2, s2, v2
	v_lshlrev_b32_e32 v103, 2, v1
	v_or_b32_e32 v1, 0x200, v0
	v_ashrrev_i32_e32 v3, 31, v2
	s_addc_u32 s7, s7, s1
	v_readlane_b32 s14, v253, 43
	s_waitcnt vmcnt(0)
	v_lshl_add_u64 v[64:65], v[2:3], 2, s[4:5]
	v_cmp_lt_u32_e64 s[0:1], s0, v1
	v_mov_b32_e32 v2, 0xfffffd00
	v_lshlrev_b32_e32 v192, 4, v198
	v_readlane_b32 s15, v253, 44
	v_cndmask_b32_e64 v2, 0, v2, s[0:1]
	v_lshl_add_u64 v[60:61], s[10:11], 0, v[192:193]
	v_lshl_add_u64 v[58:59], s[14:15], 0, v[192:193]
	v_lshl_add_u64 v[62:63], s[8:9], 0, v[192:193]
	v_add_u32_e32 v192, v2, v1
	v_bfe_u32 v1, v192, 6, 10
	v_add_u32_e32 v2, s2, v1
	v_ashrrev_i32_e32 v3, 31, v2
	v_lshl_add_u64 v[74:75], v[2:3], 2, s[4:5]
	v_add_u32_e32 v2, 0x100, v0
	v_lshrrev_b32_e32 v1, 6, v2
	v_add_u32_e32 v4, s2, v1
	v_ashrrev_i32_e32 v5, 31, v4
	v_readlane_b32 s2, v253, 36
	v_lshlrev_b64 v[66:67], 1, v[192:193]
	v_lshl_add_u64 v[76:77], v[4:5], 2, s[4:5]
	v_lshlrev_b32_e32 v4, 5, v198
	v_mov_b32_e32 v5, v193
	v_lshl_add_u64 v[80:81], v[192:193], 2, s[6:7]
	v_lshlrev_b32_e32 v192, 1, v2
	s_lshl_b32 s2, s2, 1
	v_readlane_b32 s4, v252, 52
	v_cndmask_b32_e64 v104, 0, 1, s[0:1]
	v_lshl_add_u64 v[68:69], s[14:15], 0, v[66:67]
	v_lshl_add_u64 v[70:71], s[10:11], 0, v[66:67]
	v_lshl_add_u64 v[72:73], s[8:9], 0, v[66:67]
	v_lshl_add_u64 v[78:79], s[6:7], 0, v[4:5]
	v_lshl_add_u64 v[82:83], s[14:15], 0, v[192:193]
	v_lshl_add_u64 v[84:85], s[10:11], 0, v[192:193]
	v_lshl_add_u64 v[86:87], s[8:9], 0, v[192:193]
	s_add_i32 s2, s4, s2
	v_lshlrev_b32_e32 v192, 1, v0
	v_lshlrev_b32_e32 v88, 1, v2
	s_mov_b32 s8, s68
	global_load_dwordx4 v[112:115], v[78:79], off offset:16
	global_load_dwordx4 v[116:119], v[78:79], off
	global_load_dwordx4 v[120:123], v[80:81], off offset:16
	global_load_dwordx4 v[124:127], v[80:81], off
	global_load_dwordx4 v[128:131], v[78:79], off offset:1040
	global_load_dwordx4 v[132:135], v[78:79], off offset:1024
	s_waitcnt vmcnt(0)
.LBB0_40:
	v_mad_i64_i32 v[0:1], s[4:5], s2, v228, v[58:59]
	global_load_dwordx4 v[42:45], v[0:1], off
	v_mad_i64_i32 v[0:1], s[4:5], s2, v228, v[60:61]
	global_load_dwordx4 v[46:49], v[0:1], off
	v_mad_i64_i32 v[0:1], s[4:5], s2, v229, v[62:63]
	s_mul_i32 s10, s2, 0x2c00
	s_mul_hi_i32 s5, s2, 0x2c00
	s_add_u32 s4, s26, s10
	s_addc_u32 s5, s27, s5
	global_load_dwordx4 v[50:53], v[0:1], off
	v_lshl_add_u64 v[0:1], s[4:5], 0, v[192:193]
	v_add_co_u32_e32 v0, vcc, s46, v0
	v_add_u32_e32 v105, s2, v104
	s_nop 0
	v_addc_co_u32_e32 v1, vcc, 0, v1, vcc
	global_load_dwordx4 v[54:57], v[0:1], off offset:2048
	s_nop 0
	global_load_dword v0, v[64:65], off
	v_mad_i64_i32 v[2:3], s[6:7], v105, s43, v[68:69]
	global_load_dwordx4 v[22:25], v[2:3], off
	v_mad_i64_i32 v[2:3], s[6:7], v105, s43, v[70:71]
	global_load_dwordx4 v[26:29], v[2:3], off
	v_mad_i64_i32 v[2:3], s[6:7], v105, s44, v[72:73]
	global_load_dwordx4 v[30:33], v[2:3], off
	v_mov_b64_e32 v[2:3], s[26:27]
	v_mad_i64_i32 v[92:93], s[6:7], v105, s45, v[2:3]
	v_lshl_add_u64 v[2:3], v[92:93], 0, v[66:67]
	v_add_co_u32_e32 v2, vcc, s46, v2
	s_add_i32 s9, s2, 1
	s_nop 0
	v_addc_co_u32_e32 v3, vcc, 0, v3, vcc
	global_load_dwordx4 v[38:41], v[2:3], off offset:2048
	global_load_dword v94, v[74:75], off
	v_mad_i64_i32 v[2:3], s[6:7], s9, v228, v[82:83]
	global_load_dwordx4 v[10:13], v[2:3], off
	v_mad_i64_i32 v[2:3], s[6:7], s9, v228, v[84:85]
	global_load_dwordx4 v[14:17], v[2:3], off
	v_mad_i64_i32 v[2:3], s[6:7], s9, v229, v[86:87]
	s_addk_i32 s10, 0x2c00
	s_mul_hi_i32 s7, s9, 0x2c00
	s_add_u32 s6, s26, s10
	s_addc_u32 s7, s27, s7
	v_mov_b32_e32 v89, v193
	global_load_dwordx4 v[18:21], v[2:3], off
	v_lshl_add_u64 v[2:3], s[6:7], 0, v[88:89]
	v_add_co_u32_e32 v2, vcc, s46, v2
	s_mul_i32 s10, s2, 0xffffe400
	s_nop 0
	v_addc_co_u32_e32 v3, vcc, 0, v3, vcc
	global_load_dwordx4 v[34:37], v[2:3], off offset:2048
	global_load_dword v96, v[76:77], off
	s_nop 0
	v_mov_b32_e32 v2, v112
	v_mov_b32_e32 v3, v113
	v_mov_b32_e32 v4, v114
	v_mov_b32_e32 v5, v115
	v_mov_b32_e32 v6, v116
	v_mov_b32_e32 v7, v117
	v_mov_b32_e32 v8, v118
	v_mov_b32_e32 v9, v119
	s_mul_hi_i32 s11, s2, 0xffffe400
	s_add_u32 s4, s4, s10
	s_addc_u32 s5, s5, s11
	s_addk_i32 s10, 0xe400
	s_waitcnt vmcnt(14)
	v_lshlrev_b32_e32 v90, 16, v45
	v_and_b32_e32 v91, 0xffff0000, v45
	s_waitcnt vmcnt(13)
	v_lshlrev_b32_e32 v98, 16, v49
	v_and_b32_e32 v99, 0xffff0000, v49
	v_pk_add_f32 v[90:91], v[90:91], v[98:99]
	v_and_b32_e32 v45, 0xffff0000, v48
	s_waitcnt vmcnt(12)
; __device__ __forceinline__ float siluf_(float x) { return x * __builtin_amdgcn_rcpf(1.f + __builtin_amdgcn_exp2f(x * -LOG2E)); }
; __global__ void __launch_bounds__(512, 2) hybrid_fwd(Params P0) {
;     ...
;                     float fa[8], fb[8], fx[8], fz[8]; unpack8(a, fa); unpack8(b, fb); unpack8(x, fx); unpack8(z, fz); float sq = 0.f;
; #pragma unroll
;                     for (int k = 0; k < 8; ++k) { const float v = (fa[k] + fb[k] + dsk * fx[k]) * siluf_(fz[k]); y[j * 8 + k] = v; sq += v * v; }
;                     if (rw) ss1 += sq; else ss0 += sq; }
	v_lshlrev_b32_e32 v106, 16, v53
	v_and_b32_e32 v107, 0xffff0000, v53
	v_and_b32_e32 v49, 0xffff0000, v52
	s_waitcnt vmcnt(11)
	v_lshlrev_b32_e32 v108, 16, v57
	v_mul_f32_e32 v1, 0xbfb8aa3b, v108
	v_exp_f32_e32 v1, v1
	v_and_b32_e32 v109, 0xffff0000, v57
	v_and_b32_e32 v53, 0xffff0000, v56
	v_add_f32_e32 v1, 1.0, v1
	v_rcp_f32_e32 v110, v1
	s_waitcnt vmcnt(10)
	v_pk_fma_f32 v[90:91], v[0:1], v[106:107], v[90:91] op_sel_hi:[0,1,1]
	v_mul_f32_e32 v1, 0xbfb8aa3b, v109
	v_exp_f32_e32 v1, v1
	v_lshlrev_b32_e32 v106, 16, v44
	v_and_b32_e32 v107, 0xffff0000, v44
	v_lshlrev_b32_e32 v44, 16, v48
	v_add_f32_e32 v1, 1.0, v1
	v_lshlrev_b32_e32 v48, 16, v52
	v_lshlrev_b32_e32 v52, 16, v56
	v_rcp_f32_e32 v111, v1
	v_mul_f32_e32 v1, 0xbfb8aa3b, v52
	v_exp_f32_e32 v1, v1
	v_pk_add_f32 v[44:45], v[106:107], v[44:45]
	v_lshlrev_b32_e32 v106, 16, v55
	v_and_b32_e32 v107, 0xffff0000, v55
	v_add_f32_e32 v1, 1.0, v1
	v_rcp_f32_e32 v56, v1
	v_pk_fma_f32 v[44:45], v[0:1], v[48:49], v[44:45] op_sel_hi:[0,1,1]
	v_mul_f32_e32 v1, 0xbfb8aa3b, v53
	v_exp_f32_e32 v1, v1
	v_pk_mul_f32 v[98:99], v[110:111], v[108:109]
	v_add_f32_e32 v1, 1.0, v1
	v_rcp_f32_e32 v57, v1
	v_mul_f32_e32 v1, 0xbfb8aa3b, v106
	v_exp_f32_e32 v1, v1
	v_pk_mul_f32 v[90:91], v[90:91], v[98:99]
	v_pk_mul_f32 v[48:49], v[56:57], v[52:53]
	v_lshlrev_b32_e32 v52, 16, v47
	v_pk_mul_f32 v[48:49], v[44:45], v[48:49]
	v_lshlrev_b32_e32 v44, 16, v43
	v_and_b32_e32 v45, 0xffff0000, v43
	v_and_b32_e32 v53, 0xffff0000, v47
	v_lshlrev_b32_e32 v56, 16, v51
	v_and_b32_e32 v57, 0xffff0000, v51
	v_add_f32_e32 v1, 1.0, v1
	v_pk_add_f32 v[44:45], v[44:45], v[52:53]
	v_rcp_f32_e32 v108, v1
	v_pk_fma_f32 v[44:45], v[0:1], v[56:57], v[44:45] op_sel_hi:[0,1,1]
	v_mul_f32_e32 v1, 0xbfb8aa3b, v107
	v_exp_f32_e32 v1, v1
	v_and_b32_e32 v43, 0xffff0000, v46
	v_and_b32_e32 v47, 0xffff0000, v50
	v_and_b32_e32 v51, 0xffff0000, v54
	v_add_f32_e32 v1, 1.0, v1
	v_rcp_f32_e32 v109, v1
	v_pk_mul_f32 v[98:99], v[90:91], v[90:91]
	v_pk_mul_f32 v[52:53], v[108:109], v[106:107]
	s_nop 0
	v_pk_mul_f32 v[52:53], v[44:45], v[52:53]
	v_lshlrev_b32_e32 v44, 16, v42
	v_and_b32_e32 v45, 0xffff0000, v42
	v_lshlrev_b32_e32 v42, 16, v46
	v_lshlrev_b32_e32 v46, 16, v50
	v_lshlrev_b32_e32 v50, 16, v54
	v_mul_f32_e32 v1, 0xbfb8aa3b, v50
	v_exp_f32_e32 v1, v1
	v_pk_add_f32 v[42:43], v[44:45], v[42:43]
	v_lshl_add_u64 v[44:45], s[4:5], 0, v[192:193]
	s_movk_i32 s4, 0xe400
	v_add_f32_e32 v1, 1.0, v1
	v_rcp_f32_e32 v54, v1
	v_pk_fma_f32 v[0:1], v[0:1], v[46:47], v[42:43] op_sel_hi:[0,1,1]
	v_mul_f32_e32 v42, 0xbfb8aa3b, v51
	v_exp_f32_e32 v42, v42
	s_waitcnt vmcnt(8)
	v_lshlrev_b32_e32 v46, 16, v29
	v_and_b32_e32 v47, 0xffff0000, v29
	s_waitcnt vmcnt(7)
	v_and_b32_e32 v29, 0xffff0000, v32
	v_add_f32_e32 v42, 1.0, v42
	v_rcp_f32_e32 v55, v42
	s_nop 0
	v_pk_mul_f32 v[42:43], v[54:55], v[50:51]
	s_waitcnt vmcnt(6)
	v_lshlrev_b32_e32 v54, 16, v41
	v_pk_mul_f32 v[0:1], v[0:1], v[42:43]
	v_lshlrev_b32_e32 v42, 16, v25
	v_and_b32_e32 v43, 0xffff0000, v25
	v_mul_f32_e32 v25, 0xbfb8aa3b, v54
	v_exp_f32_e32 v25, v25
	v_and_b32_e32 v55, 0xffff0000, v41
	v_lshlrev_b32_e32 v50, 16, v33
	v_and_b32_e32 v51, 0xffff0000, v33
	v_add_f32_e32 v25, 1.0, v25
	v_rcp_f32_e32 v56, v25
	v_mul_f32_e32 v25, 0xbfb8aa3b, v55
	v_exp_f32_e32 v25, v25
	v_pk_add_f32 v[42:43], v[42:43], v[46:47]
	v_and_b32_e32 v33, 0xffff0000, v40
	s_waitcnt vmcnt(5)
	v_pk_fma_f32 v[42:43], v[94:95], v[50:51], v[42:43] op_sel_hi:[0,1,1]
	v_add_f32_e32 v25, 1.0, v25
	v_rcp_f32_e32 v57, v25
	v_lshlrev_b32_e32 v50, 16, v24
	v_and_b32_e32 v51, 0xffff0000, v24
	v_lshlrev_b32_e32 v24, 16, v28
	v_and_b32_e32 v25, 0xffff0000, v28
	v_lshlrev_b32_e32 v28, 16, v32
	v_lshlrev_b32_e32 v32, 16, v40
	v_pk_add_f32 v[24:25], v[50:51], v[24:25]
	v_mul_f32_e32 v40, 0xbfb8aa3b, v32
	v_pk_fma_f32 v[24:25], v[94:95], v[28:29], v[24:25] op_sel_hi:[0,1,1]
	v_mul_f32_e32 v28, 0xbfb8aa3b, v33
	v_exp_f32_e32 v40, v40
	v_exp_f32_e32 v28, v28
	v_lshlrev_b32_e32 v50, 16, v39
	v_and_b32_e32 v51, 0xffff0000, v39
	v_add_f32_e32 v40, 1.0, v40
	v_add_f32_e32 v28, 1.0, v28
	v_rcp_f32_e32 v40, v40
	v_rcp_f32_e32 v41, v28
	v_pk_mul_f32 v[46:47], v[56:57], v[54:55]
	v_pk_mul_f32 v[28:29], v[40:41], v[32:33]
	s_nop 0
	v_pk_mul_f32 v[28:29], v[24:25], v[28:29]
	v_lshlrev_b32_e32 v24, 16, v23
	v_and_b32_e32 v25, 0xffff0000, v23
	v_mul_f32_e32 v23, 0xbfb8aa3b, v50
	v_exp_f32_e32 v23, v23
	v_lshlrev_b32_e32 v32, 16, v27
	v_and_b32_e32 v33, 0xffff0000, v27
	v_lshlrev_b32_e32 v40, 16, v31
	v_add_f32_e32 v23, 1.0, v23
	v_rcp_f32_e32 v54, v23
	v_mul_f32_e32 v23, 0xbfb8aa3b, v51
	v_exp_f32_e32 v23, v23
	v_and_b32_e32 v41, 0xffff0000, v31
	v_pk_add_f32 v[24:25], v[24:25], v[32:33]
	v_and_b32_e32 v27, 0xffff0000, v30
	v_add_f32_e32 v23, 1.0, v23
	v_rcp_f32_e32 v55, v23
	v_pk_fma_f32 v[24:25], v[94:95], v[40:41], v[24:25] op_sel_hi:[0,1,1]
	v_and_b32_e32 v23, 0xffff0000, v26
	v_and_b32_e32 v31, 0xffff0000, v38
	v_pk_mul_f32 v[32:33], v[54:55], v[50:51]
	v_mov_b32_e32 v50, v1
	v_pk_mul_f32 v[32:33], v[24:25], v[32:33]
	v_lshlrev_b32_e32 v24, 16, v22
	v_and_b32_e32 v25, 0xffff0000, v22
	v_lshlrev_b32_e32 v22, 16, v26
	v_lshlrev_b32_e32 v26, 16, v30
	v_lshlrev_b32_e32 v30, 16, v38
	v_mul_f32_e32 v38, 0xbfb8aa3b, v30
	v_pk_add_f32 v[22:23], v[24:25], v[22:23]
	v_mul_f32_e32 v24, 0xbfb8aa3b, v31
	v_exp_f32_e32 v38, v38
	v_exp_f32_e32 v24, v24
	v_pk_fma_f32 v[22:23], v[94:95], v[26:27], v[22:23] op_sel_hi:[0,1,1]
	v_mov_b32_e32 v40, v0
	v_add_f32_e32 v38, 1.0, v38
	v_add_f32_e32 v24, 1.0, v24
	v_rcp_f32_e32 v38, v38
	v_rcp_f32_e32 v39, v24
	v_pk_mul_f32 v[42:43], v[42:43], v[46:47]
	v_pk_mul_f32 v[24:25], v[38:39], v[30:31]
	s_nop 0
	v_pk_mul_f32 v[26:27], v[22:23], v[24:25]
	v_mov_b32_e32 v30, v52
	v_mov_b32_e32 v51, v27
	v_mov_b32_e32 v41, v26
	v_pk_mul_f32 v[50:51], v[50:51], v[50:51]
	v_mov_b32_e32 v31, v32
	v_pk_fma_f32 v[40:41], v[40:41], v[40:41], v[50:51]
	v_mov_b32_e32 v38, v53
	v_mov_b32_e32 v39, v33
	v_pk_fma_f32 v[30:31], v[30:31], v[30:31], v[40:41]
	v_mov_b32_e32 v22, v48
	v_mov_b32_e32 v23, v28
	v_pk_fma_f32 v[30:31], v[38:39], v[38:39], v[30:31]
	v_pk_mul_f32 v[46:47], v[42:43], v[42:43]
	v_mov_b32_e32 v24, v49
	v_mov_b32_e32 v25, v29
	v_pk_fma_f32 v[22:23], v[22:23], v[22:23], v[30:31]
	s_waitcnt vmcnt(1)
; __device__ __forceinline__ float siluf_(float x) { return x * __builtin_amdgcn_rcpf(1.f + __builtin_amdgcn_exp2f(x * -LOG2E)); }
; __global__ void __launch_bounds__(512, 2) hybrid_fwd(Params P0) {
;     ...
;                     for (int k = 0; k < 8; ++k) { const float v = (fa[k] + fb[k] + dsk * fx[k]) * siluf_(fz[k]); y[j * 8 + k] = v; sq += v * v; }
;                     if (rw) ss1 += sq; else ss0 += sq; }
;                 const float r0 = rsqrtf(wave_sum(ss0) * (1.f / SSD_W) + EPS), r1 = rsqrtf(wave_sum(ss1) * (1.f / SSD_W) + EPS);
	v_lshlrev_b32_e32 v50, 16, v37
	v_pk_fma_f32 v[22:23], v[24:25], v[24:25], v[22:23]
	v_mov_b32_e32 v24, v98
	v_mov_b32_e32 v25, v46
	v_pk_add_f32 v[22:23], v[22:23], v[24:25]
	v_mov_b32_e32 v46, v99
	v_pk_add_f32 v[22:23], v[22:23], v[46:47]
	v_and_b32_e32 v51, 0xffff0000, v37
	v_cndmask_b32_e64 v30, 0, v23, s[0:1]
	v_add_f32_e32 v23, v22, v23
	v_cndmask_b32_e64 v31, v23, v22, s[0:1]
	v_mad_i64_i32 v[22:23], s[4:5], v105, s4, v[92:93]
	v_lshl_add_u64 v[24:25], v[22:23], 0, v[66:67]
	v_lshlrev_b32_e32 v22, 16, v13
	v_and_b32_e32 v23, 0xffff0000, v13
	v_mul_f32_e32 v13, 0xbfb8aa3b, v50
	v_exp_f32_e32 v13, v13
	v_lshlrev_b32_e32 v40, 16, v17
	v_and_b32_e32 v41, 0xffff0000, v17
	v_lshlrev_b32_e32 v46, 16, v21
	v_add_f32_e32 v13, 1.0, v13
	v_rcp_f32_e32 v54, v13
	v_mul_f32_e32 v13, 0xbfb8aa3b, v51
	v_exp_f32_e32 v13, v13
	v_and_b32_e32 v47, 0xffff0000, v21
	v_pk_add_f32 v[22:23], v[22:23], v[40:41]
	v_and_b32_e32 v17, 0xffff0000, v20
	v_add_f32_e32 v13, 1.0, v13
	s_waitcnt vmcnt(0)
	v_pk_fma_f32 v[22:23], v[96:97], v[46:47], v[22:23] op_sel_hi:[0,1,1]
	v_rcp_f32_e32 v55, v13
	v_lshlrev_b32_e32 v46, 16, v12
	v_and_b32_e32 v47, 0xffff0000, v12
	v_lshlrev_b32_e32 v12, 16, v16
	v_and_b32_e32 v13, 0xffff0000, v16
	v_lshlrev_b32_e32 v16, 16, v20
	v_lshlrev_b32_e32 v20, 16, v36
	v_and_b32_e32 v21, 0xffff0000, v36
	v_pk_add_f32 v[12:13], v[46:47], v[12:13]
	v_mul_f32_e32 v36, 0xbfb8aa3b, v20
	v_pk_fma_f32 v[12:13], v[96:97], v[16:17], v[12:13] op_sel_hi:[0,1,1]
	v_mul_f32_e32 v16, 0xbfb8aa3b, v21
	v_exp_f32_e32 v36, v36
	v_exp_f32_e32 v16, v16
	v_pk_mul_f32 v[40:41], v[54:55], v[50:51]
	v_lshlrev_b32_e32 v50, 16, v35
	v_add_f32_e32 v36, 1.0, v36
	v_add_f32_e32 v16, 1.0, v16
	v_rcp_f32_e32 v36, v36
	v_rcp_f32_e32 v37, v16
	v_and_b32_e32 v51, 0xffff0000, v35
	v_lshlrev_b32_e32 v46, 16, v19
	v_and_b32_e32 v47, 0xffff0000, v19
	v_pk_mul_f32 v[16:17], v[36:37], v[20:21]
	v_lshlrev_b32_e32 v36, 16, v15
	v_pk_mul_f32 v[12:13], v[12:13], v[16:17]
	v_lshlrev_b32_e32 v16, 16, v11
	v_and_b32_e32 v17, 0xffff0000, v11
	v_mul_f32_e32 v11, 0xbfb8aa3b, v50
	v_exp_f32_e32 v11, v11
	v_and_b32_e32 v37, 0xffff0000, v15
	v_pk_add_f32 v[16:17], v[16:17], v[36:37]
	v_and_b32_e32 v15, 0xffff0000, v18
	v_add_f32_e32 v11, 1.0, v11
	v_rcp_f32_e32 v54, v11
	v_mul_f32_e32 v11, 0xbfb8aa3b, v51
	v_exp_f32_e32 v11, v11
	v_pk_fma_f32 v[16:17], v[96:97], v[46:47], v[16:17] op_sel_hi:[0,1,1]
	v_lshlrev_b32_e32 v46, 16, v10
	v_and_b32_e32 v47, 0xffff0000, v10
	v_add_f32_e32 v11, 1.0, v11
	v_rcp_f32_e32 v55, v11
	v_lshlrev_b32_e32 v10, 16, v14
	v_and_b32_e32 v11, 0xffff0000, v14
	v_lshlrev_b32_e32 v14, 16, v18
	v_lshlrev_b32_e32 v18, 16, v34
	v_and_b32_e32 v19, 0xffff0000, v34
	v_pk_add_f32 v[10:11], v[46:47], v[10:11]
	v_mul_f32_e32 v34, 0xbfb8aa3b, v18
	v_pk_fma_f32 v[10:11], v[96:97], v[14:15], v[10:11] op_sel_hi:[0,1,1]
	v_mul_f32_e32 v14, 0xbfb8aa3b, v19
	v_exp_f32_e32 v34, v34
	v_exp_f32_e32 v14, v14
	v_pk_mul_f32 v[36:37], v[54:55], v[50:51]
	v_pk_mul_f32 v[20:21], v[12:13], v[12:13]
	v_add_f32_e32 v34, 1.0, v34
	v_add_f32_e32 v14, 1.0, v14
	v_rcp_f32_e32 v34, v34
	v_rcp_f32_e32 v35, v14
	v_pk_mul_f32 v[16:17], v[16:17], v[36:37]
	v_pk_mul_f32 v[22:23], v[22:23], v[40:41]
	v_pk_mul_f32 v[36:37], v[16:17], v[16:17]
	v_pk_mul_f32 v[14:15], v[34:35], v[18:19]
	v_pk_mul_f32 v[40:41], v[22:23], v[22:23]
	v_pk_mul_f32 v[10:11], v[10:11], v[14:15]
	ds_bpermute_b32 v39, v95, v31
	v_pk_mul_f32 v[14:15], v[10:11], v[10:11]
	s_mov_b32 s4, 0x3aaaaaab
	v_add_f32_e32 v14, v14, v15
	v_add_f32_e32 v14, v14, v36
	v_add_f32_e32 v14, v14, v37
	v_add_f32_e32 v14, v14, v20
	v_add_f32_e32 v14, v14, v21
	v_add_f32_e32 v14, v14, v40
	v_add_f32_e32 v14, v14, v41
	v_add_f32_e32 v30, v30, v14
	ds_bpermute_b32 v38, v95, v30
	s_waitcnt lgkmcnt(0)
	v_pk_add_f32 v[14:15], v[30:31], v[38:39]
	ds_bpermute_b32 v19, v97, v15
	ds_bpermute_b32 v18, v97, v14
	s_waitcnt lgkmcnt(0)
; __device__ __forceinline__ unsigned cvtpk(float lo, float hi) { f32x2 v = {lo, hi}; bf16x2_t b = __builtin_convertvector(v, bf16x2_t); return __builtin_bit_cast(unsigned, b); }
; __global__ void __launch_bounds__(512, 2) hybrid_fwd(Params P0) {
;     ...
;                 const float r0 = rsqrtf(wave_sum(ss0) * (1.f / SSD_W) + EPS), r1 = rsqrtf(wave_sum(ss1) * (1.f / SSD_W) + EPS);
; #pragma unroll
;                 for (int j = 0; j < 3; ++j) { const int f = (j * 64 + lane) * 8, rw = f >= SSD_W ? 1 : 0, c0 = f - rw * SSD_W; const float rstd = rw ? r1 : r0;
;                     const f32x4 g0 = *(const f32x4*)(P.in[I_SSDNG] + L * SSD_W + c0), g1 = *(const f32x4*)(P.in[I_SSDNG] + L * SSD_W + c0 + 4);
;                     u32x4 w; w.x = cvtpk(y[j * 8] * rstd * g0.x, y[j * 8 + 1] * rstd * g0.y); w.y = cvtpk(y[j * 8 + 2] * rstd * g0.z, y[j * 8 + 3] * rstd * g0.w);
;                     w.z = cvtpk(y[j * 8 + 4] * rstd * g1.x, y[j * 8 + 5] * rstd * g1.y); w.w = cvtpk(y[j * 8 + 6] * rstd * g1.z, y[j * 8 + 7] * rstd * g1.w);
;                     *(u32x4*)(mix + (size_t)(m + rw) * DM + 512 + c0) = w; }
	v_pk_add_f32 v[14:15], v[14:15], v[18:19]
	ds_bpermute_b32 v19, v100, v15
	ds_bpermute_b32 v18, v100, v14
	s_waitcnt lgkmcnt(0)
	v_pk_add_f32 v[14:15], v[14:15], v[18:19]
	ds_bpermute_b32 v19, v101, v15
	ds_bpermute_b32 v18, v101, v14
	s_waitcnt lgkmcnt(0)
	v_pk_add_f32 v[14:15], v[14:15], v[18:19]
	ds_bpermute_b32 v19, v102, v15
	ds_bpermute_b32 v18, v102, v14
	s_waitcnt lgkmcnt(0)
	v_pk_add_f32 v[14:15], v[14:15], v[18:19]
	ds_bpermute_b32 v19, v103, v15
	ds_bpermute_b32 v18, v103, v14
	s_waitcnt lgkmcnt(0)
	v_pk_add_f32 v[14:15], v[14:15], v[18:19]
	s_nop 0
	v_pk_fma_f32 v[14:15], v[14:15], s[4:5], v[194:195] op_sel_hi:[1,0,0]
	s_nop 0
	v_mul_f32_e32 v18, 0x4b800000, v15
	v_cmp_gt_f32_e64 s[4:5], s72, v15
	v_cmp_gt_f32_e32 vcc, s72, v14
	s_nop 0
	v_cndmask_b32_e64 v15, v15, v18, s[4:5]
	v_rsq_f32_e32 v15, v15
	s_nop 0
	v_mul_f32_e32 v18, 0x45800000, v15
	v_cndmask_b32_e64 v18, v15, v18, s[4:5]
	v_pk_mul_f32 v[0:1], v[0:1], v[18:19] op_sel_hi:[1,0]
	v_pk_mul_f32 v[0:1], v[0:1], v[6:7]
	v_pk_mul_f32 v[6:7], v[52:53], v[18:19] op_sel_hi:[1,0]
	v_cvt_pk_bf16_f32 v0, v0, v1
	v_pk_mul_f32 v[6:7], v[6:7], v[8:9]
	v_mul_f32_e32 v8, 0x4b800000, v14
	v_cvt_pk_bf16_f32 v1, v6, v7
	v_pk_mul_f32 v[6:7], v[48:49], v[18:19] op_sel_hi:[1,0]
	v_cndmask_b32_e32 v8, v14, v8, vcc
	v_pk_mul_f32 v[2:3], v[6:7], v[2:3]
	v_pk_mul_f32 v[6:7], v[90:91], v[18:19] op_sel_hi:[1,0]
	v_cvt_pk_bf16_f32 v2, v2, v3
	v_pk_mul_f32 v[4:5], v[6:7], v[4:5]
	v_rsq_f32_e32 v8, v8
	v_cvt_pk_bf16_f32 v3, v4, v5
	v_add_co_u32_e64 v4, s[4:5], s47, v44
	v_mul_f32_e32 v9, 0x45800000, v8
	s_nop 0
	v_addc_co_u32_e64 v5, s[4:5], 0, v45, s[4:5]
	global_store_dwordx4 v[4:5], v[0:3], off offset:1024
	s_nop 1
	v_mov_b32_e32 v0, v120
	v_mov_b32_e32 v1, v121
	v_mov_b32_e32 v2, v122
	v_mov_b32_e32 v3, v123
	s_nop 0
	v_mov_b32_e32 v4, v124
	v_mov_b32_e32 v5, v125
	v_mov_b32_e32 v6, v126
	v_mov_b32_e32 v7, v127
	v_cndmask_b32_e32 v8, v8, v9, vcc
	v_cndmask_b32_e64 v14, v18, v8, s[0:1]
	v_pk_mul_f32 v[18:19], v[26:27], v[14:15] op_sel_hi:[1,0]
	v_pk_mul_f32 v[10:11], v[10:11], v[8:9] op_sel_hi:[1,0]
	s_mul_hi_i32 s5, s9, 0xffffe400
	s_add_u32 s4, s6, s10
	s_addc_u32 s5, s7, s5
	s_add_i32 s8, s8, s86
	s_add_i32 s2, s2, s41
	s_cmpk_gt_i32 s8, 0x4fff
	v_pk_mul_f32 v[4:5], v[18:19], v[4:5]
	v_pk_mul_f32 v[18:19], v[32:33], v[14:15] op_sel_hi:[1,0]
	v_cvt_pk_bf16_f32 v4, v4, v5
	v_pk_mul_f32 v[6:7], v[18:19], v[6:7]
	s_nop 0
	v_cvt_pk_bf16_f32 v5, v6, v7
	v_pk_mul_f32 v[6:7], v[28:29], v[14:15] op_sel_hi:[1,0]
	s_nop 0
	v_pk_mul_f32 v[0:1], v[6:7], v[0:1]
	s_nop 0
	v_cvt_pk_bf16_f32 v6, v0, v1
	v_pk_mul_f32 v[0:1], v[42:43], v[14:15] op_sel_hi:[1,0]
	s_nop 0
	v_pk_mul_f32 v[0:1], v[0:1], v[2:3]
	s_nop 0
	v_cvt_pk_bf16_f32 v7, v0, v1
	v_add_co_u32_e32 v0, vcc, s47, v24
	s_nop 1
	v_addc_co_u32_e32 v1, vcc, 0, v25, vcc
	global_store_dwordx4 v[0:1], v[4:7], off offset:1024
	s_nop 1
	v_mov_b32_e32 v0, v128
	v_mov_b32_e32 v1, v129
	v_mov_b32_e32 v2, v130
	v_mov_b32_e32 v3, v131
	s_nop 0
	v_mov_b32_e32 v4, v132
	v_mov_b32_e32 v5, v133
	v_mov_b32_e32 v6, v134
	v_mov_b32_e32 v7, v135
	v_pk_mul_f32 v[4:5], v[10:11], v[4:5]
	v_pk_mul_f32 v[10:11], v[16:17], v[8:9] op_sel_hi:[1,0]
	v_cvt_pk_bf16_f32 v4, v4, v5
	v_pk_mul_f32 v[6:7], v[10:11], v[6:7]
	s_nop 0
	v_cvt_pk_bf16_f32 v5, v6, v7
	v_pk_mul_f32 v[6:7], v[12:13], v[8:9] op_sel_hi:[1,0]
	s_nop 0
	v_pk_mul_f32 v[0:1], v[6:7], v[0:1]
	s_nop 0
	v_cvt_pk_bf16_f32 v6, v0, v1
	v_pk_mul_f32 v[0:1], v[22:23], v[8:9] op_sel_hi:[1,0]
	s_nop 0
	v_pk_mul_f32 v[0:1], v[0:1], v[2:3]
	s_nop 0
	v_cvt_pk_bf16_f32 v7, v0, v1
	v_lshl_add_u64 v[0:1], s[4:5], 0, v[88:89]
	v_add_co_u32_e32 v0, vcc, 0x2c600000, v0
	s_nop 1
	v_addc_co_u32_e32 v1, vcc, 0, v1, vcc
	global_store_dwordx4 v[0:1], v[4:7], off offset:1024
	s_cbranch_scc0 .LBB0_40

; #define LAS __attribute__((address_space(3)))
; __device__ __forceinline__ int opaque_tid() { int t = threadIdx.x; asm volatile("" : "+v"(t)); return t; }
; #define MFMA32(a, b, c) __builtin_amdgcn_mfma_f32_32x32x16_bf16((a), (b), (c), 0, 0, 0)
; __device__ __forceinline__ void ssd_item(CP& P, int L, int sq, int hd, int dir, LAS unsigned char* lds) {
;     const int tid = opaque_tid(), lane = tid & 63, wid = __builtin_amdgcn_readfirstlane(tid >> 6), r = lane & 31, hi = lane >> 5;
;     int sstart, slen; seq_of(sq, sstart, slen); const int nc = slen / 128, g = hd / 6;
;     const bf16_t* xbc = (const bf16_t*)(P.ws + WS_XBC); const float* DT = (const float*)(P.ws + WS_DT);
;     bf16_t* Y = (bf16_t*)(P.ws + (dir ? WS_YB : WS_YF));
;     const float Aneg = -__expf(P.in[I_ALOG][L * 24 + dir * 12 + hd]), dtb = P.in[I_DTB][L * 24 + dir * 12 + hd]; const int dcol = dir * 12 + hd;
;     LAS float* AS = (LAS float*)(lds + S_AS); LAS float* DTV = (LAS float*)(lds + S_DTV);
;     f32x16 st;
; #pragma unroll
;     for (int i = 0; i < 16; ++i) st[i] = 0.f;
;     for (int i = tid; i < 64 * SP / 4; i += 512) ((LAS unsigned*)(lds + S_PV))[i] = 0u;
;     const int crow_ = tid >> 4, cch = tid & 15;
;     const int xrow_ = tid >> 3, xch = tid & 7;
;     const int lb = wid >> 1, pb = wid & 1, nb = wid >> 1;
;     const int trq = (lane & 15) >> 2, trb = ((lane >> 4) & 1) * 32 + (lane & 3) * 8;
;     const int xdo = S_XD + (8 * hi + trq) * SXP + 64 * pb + trb;
;     const int bdo = S_BD + (8 * hi + trq) * SP + 64 * nb + trb;
;     ...
;             const int sb0 = dir ? lb : 0, sb1 = dir ? 4 : lb + 1;
; #pragma unroll
;             for (int sb = 0; sb < 4; ++sb) if (sb >= sb0 && sb < sb1) {
;                 f32x16 cb;
; #pragma unroll
;                 for (int i = 0; i < 16; ++i) cb[i] = 0.f;
; #pragma unroll
;                 for (int ks = 0; ks < 8; ++ks) { const bf16x8 av = *(const LAS bf16x8*)(lds + S_BM + (32 * sb + r) * SP + (16 * ks + 8 * hi) * 2);
;                     const bf16x8 bv2 = *(const LAS bf16x8*)(lds + S_CM + lrow * SP + (16 * ks + 8 * hi) * 2); cb = MFMA32(av, bv2, cb); }
; #pragma unroll
;                 for (int i = 0; i < 16; ++i) { const int sr = 32 * sb + crow(i, hi); const bool ok = dir ? (sr >= lrow) : (sr <= lrow); const float gv = cb[i] * __expf(a_l - AS[sr]); cb[i] = ok ? gv : 0.f; }
.LBB0_93:
	s_ashr_i32 s18, s14, 7
	s_bfe_u32 s14, s14, 0x10006
	s_lshl_b32 s15, s14, 6
	s_lshl_b32 s16, s18, 6
	v_mad_i64_i32 v[88:89], s[4:5], v15, s44, 0
	v_mad_i64_i32 v[90:91], s[4:5], v17, s44, 0
	v_mad_i64_i32 v[92:93], s[4:5], v20, s44, 0
	v_mad_i64_i32 v[94:95], s[4:5], v21, s44, 0
	v_mad_i64_i32 v[96:97], s[4:5], v16, s44, 0
	v_mad_i64_i32 v[98:99], s[4:5], v22, s44, 0
	s_and_b64 s[4:5], s[40:41], exec
	s_mov_b32 s4, 0xaa00000
	s_cselect_b32 s4, 0x6e00000, s4
	v_lshlrev_b32_e32 v8, 3, v5
	s_add_u32 s17, s26, s4
	v_lshlrev_b32_e32 v3, 1, v5
	v_and_b32_e32 v8, 24, v8
	s_addc_u32 s21, s27, 0
	s_add_i32 s4, 0, 0x11000
	s_add_i32 s20, 0, 0x19800
	s_add_i32 s19, s18, 1
	v_and_or_b32 v3, v3, 32, v8
	v_add_u32_e32 v8, s4, v192
	s_and_b64 s[4:5], s[40:41], exec
	v_lshrrev_b32_e32 v10, 5, v105
	v_bfe_u32 v4, v5, 2, 2
	v_and_b32_e32 v23, 31, v5
	s_waitcnt vmcnt(11)
	v_mul_f32_e32 v5, 0x3fb8aa3b, v6
	v_lshl_add_u32 v9, v7, 4, s20
	s_cselect_b32 s19, s19, 4
	s_add_i32 s20, s20, s15
	v_lshlrev_b32_e32 v12, 3, v10
	v_exp_f32_e32 v108, v5
	v_lshl_or_b32 v19, s18, 5, v23
	v_lshlrev_b32_e32 v5, 4, v10
	v_lshlrev_b32_e32 v18, 2, v10
	v_add_u32_e32 v10, s20, v3
	s_lshl_b32 s20, s14, 5
	v_readlane_b32 s4, v254, 10
	v_readlane_b32 s14, v252, 61
	s_movk_i32 s25, 0x110
	v_add_u32_e32 v110, s4, v19
	s_add_u32 s4, s17, s8
	s_addc_u32 s5, s21, s9
	v_or_b32_e32 v11, s20, v23
	v_mov_b32_e32 v13, s14
	s_add_u32 s4, s4, s15
	v_mad_u32_u24 v11, v11, s25, v13
	s_addc_u32 s5, s5, 0
	v_mov_b32_e32 v13, v193
	v_or_b32_e32 v14, v12, v4
	v_lshl_add_u64 v[100:101], s[4:5], 0, v[12:13]
	s_movk_i32 s4, 0x90
	v_mad_u32_u24 v13, v14, s4, 0
	v_lshlrev_b32_e32 v14, 7, v14
	v_add_u32_e32 v12, s15, v13
	v_add3_u32 v13, v13, v14, s16
	v_lshl_add_u32 v14, v19, 1, s14
	s_lshl_b64 s[0:1], s[0:1], 2
	v_readlane_b32 s14, v254, 0
	v_readlane_b32 s15, v254, 1
	s_add_u32 s0, s14, s0
	s_addc_u32 s1, s15, s1
	v_readlane_b32 s24, v252, 62
	v_writelane_b32 v254, s0, 11
	s_cmp_lt_i32 s18, 1
	v_cmp_le_i32_e32 vcc, v18, v19
	v_writelane_b32 v254, s1, 12
	v_lshl_add_u32 v119, v20, 2, s24
	s_cselect_b64 s[0:1], -1, 0
	v_cndmask_b32_e64 v20, 0, 1, vcc
	v_cmp_ge_i32_e32 vcc, v18, v19
	v_lshlrev_b32_e32 v24, 2, v105
	v_lshl_add_u32 v120, v21, 2, s24
	s_or_b64 s[0:1], s[40:41], s[0:1]
	v_cndmask_b32_e64 v21, 0, 1, vcc
	v_or_b32_e32 v25, 0x100, v24
	v_readlane_b32 s5, v252, 63
	s_cmp_gt_i32 s19, 0
	v_cndmask_b32_e64 v20, v21, v20, s[40:41]
	v_add_u32_e32 v115, s5, v24
	v_add_u32_e32 v116, s5, v25
	v_lshl_add_u32 v118, v17, 2, s24
	v_lshl_add_u32 v121, v16, 2, s5
	v_mul_lo_u32 v17, v16, s4
	v_lshl_add_u32 v122, v22, 2, s5
	s_cselect_b64 s[4:5], -1, 0
	v_and_b32_e32 v20, 1, v20
	s_and_b64 s[4:5], s[0:1], s[4:5]
	v_cmp_eq_u32_e64 s[0:1], 1, v20
	v_or_b32_e32 v20, 1, v18
	v_cmp_lt_i32_e32 vcc, v18, v19
	v_writelane_b32 v254, s0, 13
	s_cmp_lt_i32 s18, 2
	v_cndmask_b32_e64 v21, 0, 1, vcc
	v_cmp_ge_i32_e32 vcc, v20, v19
	v_writelane_b32 v254, s1, 14
	v_mad_u32_u24 v16, v23, s25, 0
	v_cndmask_b32_e64 v20, 0, 1, vcc
	v_cndmask_b32_e64 v20, v20, v21, s[40:41]
	v_and_b32_e32 v20, 1, v20
	v_cmp_eq_u32_e64 s[0:1], 1, v20
	v_or_b32_e32 v20, 2, v18
	v_cmp_le_i32_e32 vcc, v20, v19
	v_writelane_b32 v254, s0, 15
	v_add_u32_e32 v111, s24, v24
	v_cndmask_b32_e64 v21, 0, 1, vcc
	v_cmp_ge_i32_e32 vcc, v20, v19
	v_writelane_b32 v254, s1, 16
	v_add_u32_e32 v114, s24, v25
	v_cndmask_b32_e64 v20, 0, 1, vcc
	v_cndmask_b32_e64 v20, v20, v21, s[40:41]
	v_and_b32_e32 v20, 1, v20
	v_cmp_eq_u32_e64 s[0:1], 1, v20
	v_or_b32_e32 v20, 3, v18
	v_cmp_le_i32_e32 vcc, v20, v19
	v_writelane_b32 v254, s0, 17
	v_or_b32_e32 v25, 51, v18
	v_cndmask_b32_e64 v21, 0, 1, vcc
	v_cmp_ge_i32_e32 vcc, v20, v19
	v_writelane_b32 v254, s1, 18
	v_or_b32_e32 v27, 56, v18
	v_cndmask_b32_e64 v20, 0, 1, vcc
	v_cndmask_b32_e64 v20, v20, v21, s[40:41]
	v_and_b32_e32 v20, 1, v20
	v_cmp_eq_u32_e64 s[0:1], 1, v20
	v_or_b32_e32 v20, 8, v18
	v_cmp_le_i32_e32 vcc, v20, v19
	v_lshl_add_u32 v124, v20, 2, s24
	v_writelane_b32 v254, s0, 19
	v_cndmask_b32_e64 v21, 0, 1, vcc
	v_cmp_ge_i32_e32 vcc, v20, v19
	v_or_b32_e32 v20, 9, v18
	v_writelane_b32 v254, s1, 20
	v_cndmask_b32_e64 v22, 0, 1, vcc
	v_cndmask_b32_e64 v21, v22, v21, s[40:41]
	v_and_b32_e32 v21, 1, v21
	v_cmp_le_i32_e32 vcc, v20, v19
	v_cmp_eq_u32_e64 s[0:1], 1, v21
	v_or_b32_e32 v30, 57, v18
	v_cndmask_b32_e64 v21, 0, 1, vcc
	v_cmp_ge_i32_e32 vcc, v20, v19
	v_writelane_b32 v254, s0, 21
	v_or_b32_e32 v32, 58, v18
	v_cndmask_b32_e64 v20, 0, 1, vcc
	v_cndmask_b32_e64 v20, v20, v21, s[40:41]
	v_and_b32_e32 v20, 1, v20
	v_writelane_b32 v254, s1, 22
	v_cmp_eq_u32_e64 s[0:1], 1, v20
	v_or_b32_e32 v20, 10, v18
	v_cmp_le_i32_e32 vcc, v20, v19
	v_writelane_b32 v254, s0, 23
	v_or_b32_e32 v34, 59, v18
	v_cndmask_b32_e64 v21, 0, 1, vcc
	v_cmp_ge_i32_e32 vcc, v20, v19
	v_writelane_b32 v254, s1, 24
	v_or_b32_e32 v36, 64, v18
	v_cndmask_b32_e64 v20, 0, 1, vcc
	v_cndmask_b32_e64 v20, v20, v21, s[40:41]
	v_and_b32_e32 v20, 1, v20
	v_cmp_eq_u32_e64 s[0:1], 1, v20
	v_or_b32_e32 v20, 11, v18
	v_cmp_le_i32_e32 vcc, v20, v19
	v_writelane_b32 v254, s0, 25
	v_or_b32_e32 v39, 0x41, v18
	v_cndmask_b32_e64 v21, 0, 1, vcc
	v_cmp_ge_i32_e32 vcc, v20, v19
	v_writelane_b32 v254, s1, 26
	v_or_b32_e32 v41, 0x42, v18
	v_cndmask_b32_e64 v20, 0, 1, vcc
	v_cndmask_b32_e64 v20, v20, v21, s[40:41]
	v_and_b32_e32 v20, 1, v20
	v_cmp_eq_u32_e64 s[0:1], 1, v20
	v_or_b32_e32 v20, 16, v18
	v_cmp_le_i32_e32 vcc, v20, v19
	v_lshl_add_u32 v125, v20, 2, s24
	v_writelane_b32 v254, s0, 27
	v_cndmask_b32_e64 v21, 0, 1, vcc
	v_cmp_ge_i32_e32 vcc, v20, v19
	v_or_b32_e32 v20, 17, v18
	v_writelane_b32 v254, s1, 28
	v_cndmask_b32_e64 v22, 0, 1, vcc
; #define LAS __attribute__((address_space(3)))
; #define MFMA32(a, b, c) __builtin_amdgcn_mfma_f32_32x32x16_bf16((a), (b), (c), 0, 0, 0)
; __device__ __forceinline__ int crow(int r, int hi) { return (r & 3) + 8 * (r >> 2) + 4 * hi; }
; __device__ __forceinline__ void ssd_item(CP& P, int L, int sq, int hd, int dir, LAS unsigned char* lds) {
;     ...
;             const int sb0 = dir ? lb : 0, sb1 = dir ? 4 : lb + 1;
; #pragma unroll
;             for (int sb = 0; sb < 4; ++sb) if (sb >= sb0 && sb < sb1) {
;                 f32x16 cb;
; #pragma unroll
;                 for (int i = 0; i < 16; ++i) cb[i] = 0.f;
; #pragma unroll
;                 for (int ks = 0; ks < 8; ++ks) { const bf16x8 av = *(const LAS bf16x8*)(lds + S_BM + (32 * sb + r) * SP + (16 * ks + 8 * hi) * 2);
;                     const bf16x8 bv2 = *(const LAS bf16x8*)(lds + S_CM + lrow * SP + (16 * ks + 8 * hi) * 2); cb = MFMA32(av, bv2, cb); }
; #pragma unroll
;                 for (int i = 0; i < 16; ++i) { const int sr = 32 * sb + crow(i, hi); const bool ok = dir ? (sr >= lrow) : (sr <= lrow); const float gv = cb[i] * __expf(a_l - AS[sr]); cb[i] = ok ? gv : 0.f; }
	v_cndmask_b32_e64 v21, v22, v21, s[40:41]
	v_and_b32_e32 v21, 1, v21
	v_cmp_le_i32_e32 vcc, v20, v19
	v_cmp_eq_u32_e64 s[0:1], 1, v21
	v_or_b32_e32 v43, 0x43, v18
	v_cndmask_b32_e64 v21, 0, 1, vcc
	v_cmp_ge_i32_e32 vcc, v20, v19
	v_writelane_b32 v254, s0, 29
	v_or_b32_e32 v45, 0x48, v18
	v_cndmask_b32_e64 v20, 0, 1, vcc
	v_cndmask_b32_e64 v20, v20, v21, s[40:41]
	v_and_b32_e32 v20, 1, v20
	v_writelane_b32 v254, s1, 30
	v_cmp_eq_u32_e64 s[0:1], 1, v20
	v_or_b32_e32 v20, 18, v18
	v_cmp_le_i32_e32 vcc, v20, v19
	v_writelane_b32 v254, s0, 31
	v_or_b32_e32 v102, 0x49, v18
	v_cndmask_b32_e64 v21, 0, 1, vcc
	v_cmp_ge_i32_e32 vcc, v20, v19
	v_writelane_b32 v254, s1, 32
	v_or_b32_e32 v131, 0x4a, v18
	v_cndmask_b32_e64 v20, 0, 1, vcc
	v_cndmask_b32_e64 v20, v20, v21, s[40:41]
	v_and_b32_e32 v20, 1, v20
	v_cmp_eq_u32_e64 s[0:1], 1, v20
	v_or_b32_e32 v20, 19, v18
	v_cmp_le_i32_e32 vcc, v20, v19
	v_writelane_b32 v254, s0, 33
	v_or_b32_e32 v138, 0x50, v18
	v_cndmask_b32_e64 v21, 0, 1, vcc
	v_cmp_ge_i32_e32 vcc, v20, v19
	v_writelane_b32 v254, s1, 34
	v_or_b32_e32 v147, 0x58, v18
	v_cndmask_b32_e64 v20, 0, 1, vcc
	v_cndmask_b32_e64 v20, v20, v21, s[40:41]
	v_and_b32_e32 v20, 1, v20
	v_cmp_eq_u32_e64 s[0:1], 1, v20
	v_or_b32_e32 v20, 24, v18
	v_cmp_le_i32_e32 vcc, v20, v19
	v_lshl_add_u32 v127, v20, 2, s24
	v_writelane_b32 v254, s0, 35
	v_cndmask_b32_e64 v21, 0, 1, vcc
	v_cmp_ge_i32_e32 vcc, v20, v19
	v_or_b32_e32 v20, 25, v18
	v_writelane_b32 v254, s1, 36
	v_cndmask_b32_e64 v22, 0, 1, vcc
	v_cndmask_b32_e64 v21, v22, v21, s[40:41]
	v_and_b32_e32 v21, 1, v21
	v_cmp_le_i32_e32 vcc, v20, v19
	v_cmp_eq_u32_e64 s[0:1], 1, v21
	v_or_b32_e32 v156, 0x60, v18
	v_cndmask_b32_e64 v21, 0, 1, vcc
	v_cmp_ge_i32_e32 vcc, v20, v19
	v_writelane_b32 v254, s0, 37
	v_or_b32_e32 v165, 0x68, v18
	v_cndmask_b32_e64 v20, 0, 1, vcc
	v_cndmask_b32_e64 v20, v20, v21, s[40:41]
	v_and_b32_e32 v20, 1, v20
	v_writelane_b32 v254, s1, 38
	v_cmp_eq_u32_e64 s[0:1], 1, v20
	v_or_b32_e32 v20, 26, v18
	v_cmp_le_i32_e32 vcc, v20, v19
	v_writelane_b32 v254, s0, 39
	v_or_b32_e32 v174, 0x70, v18
	v_cndmask_b32_e64 v21, 0, 1, vcc
	v_cmp_ge_i32_e32 vcc, v20, v19
	v_writelane_b32 v254, s1, 40
	v_or_b32_e32 v183, 0x78, v18
	v_cndmask_b32_e64 v20, 0, 1, vcc
	v_cndmask_b32_e64 v20, v20, v21, s[40:41]
	v_and_b32_e32 v20, 1, v20
	v_cmp_eq_u32_e64 s[0:1], 1, v20
	v_or_b32_e32 v20, 27, v18
	v_cmp_le_i32_e32 vcc, v20, v19
	v_writelane_b32 v254, s0, 41
	v_lshl_add_u32 v133, v45, 2, s24
	v_cndmask_b32_e64 v21, 0, 1, vcc
	v_cmp_ge_i32_e32 vcc, v20, v19
	v_writelane_b32 v254, s1, 42
	v_lshlrev_b32_e32 v2, 3, v7
	v_cndmask_b32_e64 v20, 0, 1, vcc
	v_cndmask_b32_e64 v20, v20, v21, s[40:41]
	v_and_b32_e32 v20, 1, v20
	v_cmp_eq_u32_e64 s[0:1], 1, v20
	v_or_b32_e32 v21, 32, v18
	v_cmp_le_i32_e32 vcc, v21, v19
	v_writelane_b32 v254, s0, 43
	v_lshl_add_u32 v109, v19, 2, s24
	v_cndmask_b32_e64 v22, 0, 1, vcc
	v_writelane_b32 v254, s1, 44
	s_cselect_b64 s[0:1], -1, 0
	v_cmp_ge_i32_e32 vcc, v21, v19
	s_or_b64 s[0:1], s[40:41], s[0:1]
	s_cmp_gt_i32 s19, 1
	v_cndmask_b32_e64 v23, 0, 1, vcc
	v_cndmask_b32_e64 v22, v23, v22, s[40:41]
	s_cselect_b64 s[14:15], -1, 0
	v_and_b32_e32 v22, 1, v22
	s_and_b64 s[14:15], s[0:1], s[14:15]
	v_cmp_eq_u32_e64 s[0:1], 1, v22
	v_or_b32_e32 v22, 33, v18
	v_cmp_le_i32_e32 vcc, v22, v19
	v_writelane_b32 v254, s0, 45
	s_cmp_lt_i32 s18, 3
	v_cndmask_b32_e64 v23, 0, 1, vcc
	v_cmp_ge_i32_e32 vcc, v22, v19
	v_writelane_b32 v254, s1, 46
	v_mul_lo_u32 v7, v19, s25
	v_cndmask_b32_e64 v22, 0, 1, vcc
	v_cndmask_b32_e64 v22, v22, v23, s[40:41]
	v_and_b32_e32 v22, 1, v22
	v_cmp_eq_u32_e64 s[0:1], 1, v22
	v_or_b32_e32 v22, 34, v18
	v_cmp_le_i32_e32 vcc, v22, v19
	v_writelane_b32 v254, s0, 47
	v_or_b32_e32 v20, v18, v4
	v_cndmask_b32_e64 v23, 0, 1, vcc
	v_cmp_ge_i32_e32 vcc, v22, v19
	v_writelane_b32 v254, s1, 48
	v_lshl_add_u32 v128, v21, 2, s24
	v_cndmask_b32_e64 v22, 0, 1, vcc
	v_cndmask_b32_e64 v22, v22, v23, s[40:41]
	v_and_b32_e32 v22, 1, v22
	v_cmp_eq_u32_e64 s[0:1], 1, v22
	v_or_b32_e32 v22, 35, v18
	v_cmp_le_i32_e32 vcc, v22, v19
	v_writelane_b32 v254, s0, 49
	v_or_b32_e32 v21, v21, v4
	v_cndmask_b32_e64 v23, 0, 1, vcc
	v_cmp_ge_i32_e32 vcc, v22, v19
	v_writelane_b32 v254, s1, 50
	v_lshl_add_u32 v132, v36, 2, s24
	v_cndmask_b32_e64 v22, 0, 1, vcc
	v_cndmask_b32_e64 v22, v22, v23, s[40:41]
	v_and_b32_e32 v22, 1, v22
	v_cmp_eq_u32_e64 s[0:1], 1, v22
	v_or_b32_e32 v22, 40, v18
	v_cmp_le_i32_e32 vcc, v22, v19
	v_lshl_add_u32 v129, v22, 2, s24
	v_writelane_b32 v254, s0, 51
	v_cndmask_b32_e64 v23, 0, 1, vcc
	v_cmp_ge_i32_e32 vcc, v22, v19
	v_or_b32_e32 v22, 41, v18
	v_writelane_b32 v254, s1, 52
	v_cndmask_b32_e64 v24, 0, 1, vcc
	v_cndmask_b32_e64 v23, v24, v23, s[40:41]
	v_and_b32_e32 v23, 1, v23
	v_cmp_le_i32_e32 vcc, v22, v19
	v_cmp_eq_u32_e64 s[0:1], 1, v23
	v_lshlrev_b32_e32 v1, 3, v1
	v_cndmask_b32_e64 v23, 0, 1, vcc
	v_cmp_ge_i32_e32 vcc, v22, v19
	v_writelane_b32 v254, s0, 53
	v_add_u32_e32 v6, 0, v192
	v_cndmask_b32_e64 v22, 0, 1, vcc
	v_cndmask_b32_e64 v22, v22, v23, s[40:41]
	v_and_b32_e32 v22, 1, v22
	v_writelane_b32 v254, s1, 54
	v_cmp_eq_u32_e64 s[0:1], 1, v22
	v_or_b32_e32 v22, 42, v18
	v_cmp_le_i32_e32 vcc, v22, v19
	v_writelane_b32 v254, s0, 55
	v_add_u32_e32 v7, 0, v7
	v_cndmask_b32_e64 v23, 0, 1, vcc
	v_cmp_ge_i32_e32 vcc, v22, v19
	v_writelane_b32 v254, s1, 56
	v_add_u32_e32 v12, 0x19800, v12
	v_cndmask_b32_e64 v22, 0, 1, vcc
	v_cndmask_b32_e64 v22, v22, v23, s[40:41]
	v_and_b32_e32 v22, 1, v22
	v_cmp_eq_u32_e64 s[0:1], 1, v22
	v_or_b32_e32 v22, 43, v18
	v_cmp_le_i32_e32 vcc, v22, v19
	v_writelane_b32 v254, s0, 57
	v_add_u32_e32 v13, 0x11000, v13
	v_cndmask_b32_e64 v23, 0, 1, vcc
; #define LAS __attribute__((address_space(3)))
; #define MFMA32(a, b, c) __builtin_amdgcn_mfma_f32_32x32x16_bf16((a), (b), (c), 0, 0, 0)
; __device__ __forceinline__ int crow(int r, int hi) { return (r & 3) + 8 * (r >> 2) + 4 * hi; }
; __device__ __forceinline__ void ssd_item(CP& P, int L, int sq, int hd, int dir, LAS unsigned char* lds) {
;     ...
;             const int sb0 = dir ? lb : 0, sb1 = dir ? 4 : lb + 1;
; #pragma unroll
;             for (int sb = 0; sb < 4; ++sb) if (sb >= sb0 && sb < sb1) {
;                 f32x16 cb;
; #pragma unroll
;                 for (int i = 0; i < 16; ++i) cb[i] = 0.f;
; #pragma unroll
;                 for (int ks = 0; ks < 8; ++ks) { const bf16x8 av = *(const LAS bf16x8*)(lds + S_BM + (32 * sb + r) * SP + (16 * ks + 8 * hi) * 2);
;                     const bf16x8 bv2 = *(const LAS bf16x8*)(lds + S_CM + lrow * SP + (16 * ks + 8 * hi) * 2); cb = MFMA32(av, bv2, cb); }
; #pragma unroll
;                 for (int i = 0; i < 16; ++i) { const int sr = 32 * sb + crow(i, hi); const bool ok = dir ? (sr >= lrow) : (sr <= lrow); const float gv = cb[i] * __expf(a_l - AS[sr]); cb[i] = ok ? gv : 0.f; }
	v_cmp_ge_i32_e32 vcc, v22, v19
	v_writelane_b32 v254, s1, 58
	v_lshl_add_u32 v117, v15, 2, s24
	v_cndmask_b32_e64 v22, 0, 1, vcc
	v_cndmask_b32_e64 v22, v22, v23, s[40:41]
	v_and_b32_e32 v22, 1, v22
	v_cmp_eq_u32_e64 s[0:1], 1, v22
	v_or_b32_e32 v22, 48, v18
	v_cmp_le_i32_e32 vcc, v22, v19
	v_lshl_add_u32 v130, v22, 2, s24
	v_writelane_b32 v254, s0, 59
	v_cndmask_b32_e64 v23, 0, 1, vcc
	v_cmp_ge_i32_e32 vcc, v22, v19
	v_or_b32_e32 v22, 49, v18
	v_writelane_b32 v254, s1, 60
	v_cndmask_b32_e64 v24, 0, 1, vcc
	v_cndmask_b32_e64 v23, v24, v23, s[40:41]
	v_and_b32_e32 v23, 1, v23
	v_cmp_le_i32_e32 vcc, v22, v19
	v_cmp_eq_u32_e64 s[0:1], 1, v23
	v_mul_lo_u32 v15, v15, s25
	v_cndmask_b32_e64 v23, 0, 1, vcc
	v_cmp_ge_i32_e32 vcc, v22, v19
	v_writelane_b32 v254, s0, 61
	v_mul_u32_u24_e32 v20, 0x90, v20
	v_cndmask_b32_e64 v22, 0, 1, vcc
	v_cndmask_b32_e64 v22, v22, v23, s[40:41]
	v_or_b32_e32 v23, 50, v18
	v_cmp_le_i32_e32 vcc, v23, v19
	v_writelane_b32 v254, s1, 62
	s_cselect_b64 s[0:1], -1, 0
	v_cndmask_b32_e64 v24, 0, 1, vcc
	v_cmp_ge_i32_e32 vcc, v23, v19
	s_or_b64 s[0:1], s[40:41], s[0:1]
	s_cmp_gt_i32 s19, 2
	v_cndmask_b32_e64 v23, 0, 1, vcc
	v_cmp_le_i32_e32 vcc, v25, v19
	s_cselect_b64 s[16:17], -1, 0
	s_and_b64 s[16:17], s[0:1], s[16:17]
	v_cndmask_b32_e64 v26, 0, 1, vcc
	v_cmp_ge_i32_e32 vcc, v25, v19
	s_cmp_lt_i32 s18, 4
	s_cselect_b64 s[0:1], -1, 0
	v_cndmask_b32_e64 v25, 0, 1, vcc
	v_cmp_le_i32_e32 vcc, v27, v19
	s_or_b64 s[0:1], s[40:41], s[0:1]
	s_cmp_gt_i32 s19, 3
	v_cndmask_b32_e64 v28, 0, 1, vcc
	v_cmp_ge_i32_e32 vcc, v27, v19
	v_and_b32_e32 v22, 1, v22
	s_cselect_b64 s[18:19], -1, 0
	v_cndmask_b32_e64 v29, 0, 1, vcc
	v_cmp_le_i32_e32 vcc, v30, v19
	s_and_b64 s[18:19], s[0:1], s[18:19]
	v_cmp_eq_u32_e64 s[0:1], 1, v22
	v_cndmask_b32_e64 v31, 0, 1, vcc
	v_cmp_ge_i32_e32 vcc, v30, v19
	v_cndmask_b32_e64 v22, v23, v24, s[40:41]
	v_writelane_b32 v254, s0, 63
	v_cndmask_b32_e64 v30, 0, 1, vcc
	v_cmp_le_i32_e32 vcc, v32, v19
	v_and_b32_e32 v22, 1, v22
	v_writelane_b32 v255, s1, 0
	v_cndmask_b32_e64 v33, 0, 1, vcc
	v_cmp_ge_i32_e32 vcc, v32, v19
	v_cmp_eq_u32_e64 s[0:1], 1, v22
	v_cndmask_b32_e64 v22, v25, v26, s[40:41]
	v_cndmask_b32_e64 v32, 0, 1, vcc
	v_cmp_le_i32_e32 vcc, v34, v19
	v_writelane_b32 v255, s0, 1
	v_and_b32_e32 v22, 1, v22
	v_cndmask_b32_e64 v35, 0, 1, vcc
	v_cmp_ge_i32_e32 vcc, v34, v19
	v_writelane_b32 v255, s1, 2
	v_cndmask_b32_e64 v23, v29, v28, s[40:41]
	v_cndmask_b32_e64 v34, 0, 1, vcc
	v_cmp_le_i32_e32 vcc, v36, v19
	v_cmp_eq_u32_e64 s[0:1], 1, v22
	v_and_b32_e32 v23, 1, v23
	v_cndmask_b32_e64 v37, 0, 1, vcc
	v_cmp_ge_i32_e32 vcc, v36, v19
	v_writelane_b32 v255, s0, 3
	v_cndmask_b32_e64 v24, v30, v31, s[40:41]
	v_cndmask_b32_e64 v38, 0, 1, vcc
	v_cmp_le_i32_e32 vcc, v39, v19
	v_writelane_b32 v255, s1, 4
	v_cmp_eq_u32_e64 s[0:1], 1, v23
	v_cndmask_b32_e64 v40, 0, 1, vcc
	v_cmp_ge_i32_e32 vcc, v39, v19
	v_and_b32_e32 v24, 1, v24
	v_writelane_b32 v255, s0, 5
	v_cndmask_b32_e64 v39, 0, 1, vcc
	v_cmp_le_i32_e32 vcc, v41, v19
	v_cndmask_b32_e64 v25, v32, v33, s[40:41]
	v_writelane_b32 v255, s1, 6
	v_cndmask_b32_e64 v42, 0, 1, vcc
	v_cmp_ge_i32_e32 vcc, v41, v19
	v_cmp_eq_u32_e64 s[0:1], 1, v24
	v_and_b32_e32 v25, 1, v25
	v_cndmask_b32_e64 v41, 0, 1, vcc
	v_cmp_le_i32_e32 vcc, v43, v19
	v_writelane_b32 v255, s0, 7
	v_cndmask_b32_e64 v26, v34, v35, s[40:41]
	v_cndmask_b32_e64 v44, 0, 1, vcc
	v_cmp_ge_i32_e32 vcc, v43, v19
	v_cndmask_b32_e64 v29, v41, v42, s[40:41]
	v_writelane_b32 v255, s1, 8
	v_cndmask_b32_e64 v43, 0, 1, vcc
	v_cmp_le_i32_e32 vcc, v45, v19
	v_cmp_eq_u32_e64 s[0:1], 1, v25
	v_and_b32_e32 v26, 1, v26
	v_cndmask_b32_e64 v46, 0, 1, vcc
	v_cmp_ge_i32_e32 vcc, v45, v19
	v_cndmask_b32_e64 v30, v43, v44, s[40:41]
	v_writelane_b32 v255, s0, 9
	v_cndmask_b32_e64 v47, 0, 1, vcc
	v_cmp_le_i32_e32 vcc, v102, v19
	v_writelane_b32 v255, s1, 10
	v_cmp_eq_u32_e64 s[0:1], 1, v26
	v_cndmask_b32_e64 v103, 0, 1, vcc
	v_cmp_ge_i32_e32 vcc, v102, v19
	v_writelane_b32 v255, s0, 11
	v_cndmask_b32_e64 v28, v39, v40, s[40:41]
	v_cndmask_b32_e64 v102, 0, 1, vcc
	v_cmp_le_i32_e32 vcc, v131, v19
	v_cndmask_b32_e64 v32, v102, v103, s[40:41]
	v_writelane_b32 v255, s1, 12
	v_cndmask_b32_e64 v134, 0, 1, vcc
	v_cmp_ge_i32_e32 vcc, v131, v19
	v_or_b32_e32 v131, 0x4b, v18
	v_and_b32_e32 v28, 1, v28
	v_cndmask_b32_e64 v135, 0, 1, vcc
	v_cmp_le_i32_e32 vcc, v131, v19
	v_and_b32_e32 v29, 1, v29
	v_cndmask_b32_e64 v31, v47, v46, s[40:41]
	v_cndmask_b32_e64 v136, 0, 1, vcc
	v_cmp_ge_i32_e32 vcc, v131, v19
	v_or_b32_e32 v131, 0x51, v18
	v_cndmask_b32_e64 v33, v135, v134, s[40:41]
	v_cndmask_b32_e64 v137, 0, 1, vcc
	v_cmp_le_i32_e32 vcc, v138, v19
	v_cndmask_b32_e64 v34, v137, v136, s[40:41]
	v_or_b32_e32 v36, v36, v4
	v_cndmask_b32_e64 v139, 0, 1, vcc
	v_cmp_ge_i32_e32 vcc, v138, v19
	v_or_b32_e32 v4, v156, v4
	v_mul_u32_u24_e32 v21, 0x90, v21
	v_cndmask_b32_e64 v140, 0, 1, vcc
	v_cmp_le_i32_e32 vcc, v131, v19
	v_cndmask_b32_e64 v35, v140, v139, s[40:41]
	v_and_b32_e32 v30, 1, v30
	v_cndmask_b32_e64 v141, 0, 1, vcc
	v_cmp_ge_i32_e32 vcc, v131, v19
	v_or_b32_e32 v131, 0x52, v18
	v_and_b32_e32 v31, 1, v31
	v_cndmask_b32_e64 v142, 0, 1, vcc
	v_cmp_le_i32_e32 vcc, v131, v19
	v_and_b32_e32 v32, 1, v32
	v_and_b32_e32 v33, 1, v33
	v_cndmask_b32_e64 v143, 0, 1, vcc
	v_cmp_ge_i32_e32 vcc, v131, v19
	v_or_b32_e32 v131, 0x53, v18
	v_and_b32_e32 v34, 1, v34
	v_cndmask_b32_e64 v144, 0, 1, vcc
	v_cmp_le_i32_e32 vcc, v131, v19
	v_and_b32_e32 v35, 1, v35
	v_mul_u32_u24_e32 v36, 0x90, v36
	v_cndmask_b32_e64 v145, 0, 1, vcc
	v_cmp_ge_i32_e32 vcc, v131, v19
	v_or_b32_e32 v131, 0x59, v18
	v_mul_u32_u24_e32 v4, 0x90, v4
	v_cndmask_b32_e64 v146, 0, 1, vcc
; #define LAS __attribute__((address_space(3)))
; #define MFMA32(a, b, c) __builtin_amdgcn_mfma_f32_32x32x16_bf16((a), (b), (c), 0, 0, 0)
; __device__ __forceinline__ int crow(int r, int hi) { return (r & 3) + 8 * (r >> 2) + 4 * hi; }
; __device__ __forceinline__ void ssd_item(CP& P, int L, int sq, int hd, int dir, LAS unsigned char* lds) {
;     ...
;             for (int o = 1; o < 64; o <<= 1) { const float t0 = __shfl_up(p0, o), t1 = __shfl_up(p1, o); if (lane >= o) { p0 += t0; p1 += t1; } }
;     ...
;             const int sb0 = dir ? lb : 0, sb1 = dir ? 4 : lb + 1;
; #pragma unroll
;             for (int sb = 0; sb < 4; ++sb) if (sb >= sb0 && sb < sb1) {
;                 f32x16 cb;
; #pragma unroll
;                 for (int i = 0; i < 16; ++i) cb[i] = 0.f;
; #pragma unroll
;                 for (int ks = 0; ks < 8; ++ks) { const bf16x8 av = *(const LAS bf16x8*)(lds + S_BM + (32 * sb + r) * SP + (16 * ks + 8 * hi) * 2);
;                     const bf16x8 bv2 = *(const LAS bf16x8*)(lds + S_CM + lrow * SP + (16 * ks + 8 * hi) * 2); cb = MFMA32(av, bv2, cb); }
; #pragma unroll
;                 for (int i = 0; i < 16; ++i) { const int sr = 32 * sb + crow(i, hi); const bool ok = dir ? (sr >= lrow) : (sr <= lrow); const float gv = cb[i] * __expf(a_l - AS[sr]); cb[i] = ok ? gv : 0.f; }
	v_cmp_le_i32_e32 vcc, v147, v19
	v_cndmask_b32_e64 v39, v146, v145, s[40:41]
	v_and_b32_e32 v39, 1, v39
	v_cndmask_b32_e64 v148, 0, 1, vcc
	v_cmp_ge_i32_e32 vcc, v147, v19
	s_mov_b32 s23, 1
	v_cmp_eq_u32_e64 s[42:43], 0, v105
	v_cndmask_b32_e64 v149, 0, 1, vcc
	v_cmp_le_i32_e32 vcc, v131, v19
	v_cndmask_b32_e64 v40, v149, v148, s[40:41]
	v_and_b32_e32 v40, 1, v40
	v_cndmask_b32_e64 v150, 0, 1, vcc
	v_cmp_ge_i32_e32 vcc, v131, v19
	v_or_b32_e32 v131, 0x5a, v18
	v_cmp_gt_u32_e64 s[44:45], 2, v105
	v_cndmask_b32_e64 v151, 0, 1, vcc
	v_cmp_le_i32_e32 vcc, v131, v19
	v_cndmask_b32_e64 v41, v151, v150, s[40:41]
	v_and_b32_e32 v41, 1, v41
	v_cndmask_b32_e64 v152, 0, 1, vcc
	v_cmp_ge_i32_e32 vcc, v131, v19
	v_or_b32_e32 v131, 0x5b, v18
	v_cmp_gt_u32_e64 s[46:47], 4, v105
	v_cndmask_b32_e64 v153, 0, 1, vcc
	v_cmp_le_i32_e32 vcc, v131, v19
	v_cndmask_b32_e64 v42, v153, v152, s[40:41]
	v_and_b32_e32 v42, 1, v42
	v_cndmask_b32_e64 v154, 0, 1, vcc
	v_cmp_ge_i32_e32 vcc, v131, v19
	v_or_b32_e32 v131, 0x61, v18
	v_cmp_gt_u32_e64 s[48:49], 8, v105
	v_cndmask_b32_e64 v155, 0, 1, vcc
	v_cmp_le_i32_e32 vcc, v156, v19
	v_cndmask_b32_e64 v43, v155, v154, s[40:41]
	v_and_b32_e32 v43, 1, v43
	v_cndmask_b32_e64 v157, 0, 1, vcc
	v_cmp_ge_i32_e32 vcc, v156, v19
	v_cmp_gt_u32_e64 s[50:51], 16, v105
	v_cmp_gt_u32_e64 s[52:53], 32, v105
	v_cndmask_b32_e64 v158, 0, 1, vcc
	v_cmp_le_i32_e32 vcc, v131, v19
	v_cndmask_b32_e64 v44, v158, v157, s[40:41]
	v_and_b32_e32 v44, 1, v44
	v_cndmask_b32_e64 v159, 0, 1, vcc
	v_cmp_ge_i32_e32 vcc, v131, v19
	v_or_b32_e32 v131, 0x62, v18
	v_add_u32_e32 v123, s24, v5
	v_cndmask_b32_e64 v160, 0, 1, vcc
	v_cmp_le_i32_e32 vcc, v131, v19
	v_cndmask_b32_e64 v45, v160, v159, s[40:41]
	v_and_b32_e32 v45, 1, v45
	v_cndmask_b32_e64 v161, 0, 1, vcc
	v_cmp_ge_i32_e32 vcc, v131, v19
	v_or_b32_e32 v131, 0x63, v18
	v_lshl_add_u32 v134, v138, 2, s24
	v_cndmask_b32_e64 v162, 0, 1, vcc
	v_cmp_le_i32_e32 vcc, v131, v19
	v_cndmask_b32_e64 v46, v162, v161, s[40:41]
	v_and_b32_e32 v46, 1, v46
	v_cndmask_b32_e64 v163, 0, 1, vcc
	v_cmp_ge_i32_e32 vcc, v131, v19
	v_or_b32_e32 v131, 0x69, v18
	v_lshl_add_u32 v135, v147, 2, s24
	v_cndmask_b32_e64 v164, 0, 1, vcc
	v_cmp_le_i32_e32 vcc, v165, v19
	v_cndmask_b32_e64 v47, v164, v163, s[40:41]
	v_and_b32_e32 v47, 1, v47
	v_cndmask_b32_e64 v166, 0, 1, vcc
	v_cmp_ge_i32_e32 vcc, v165, v19
	v_lshl_add_u32 v136, v156, 2, s24
	v_lshl_add_u32 v137, v165, 2, s24
	v_cndmask_b32_e64 v167, 0, 1, vcc
	v_cmp_le_i32_e32 vcc, v131, v19
	v_cndmask_b32_e64 v102, v167, v166, s[40:41]
	v_and_b32_e32 v103, 1, v102
	v_cndmask_b32_e64 v168, 0, 1, vcc
	v_cmp_ge_i32_e32 vcc, v131, v19
	v_or_b32_e32 v131, 0x6a, v18
	v_lshl_add_u32 v138, v174, 2, s24
	v_cndmask_b32_e64 v169, 0, 1, vcc
	v_cmp_le_i32_e32 vcc, v131, v19
	v_cndmask_b32_e64 v102, v169, v168, s[40:41]
	v_and_b32_e32 v153, 1, v102
	v_cndmask_b32_e64 v170, 0, 1, vcc
	v_cmp_ge_i32_e32 vcc, v131, v19
	v_or_b32_e32 v131, 0x6b, v18
	v_lshl_add_u32 v139, v183, 2, s24
	v_cndmask_b32_e64 v171, 0, 1, vcc
	v_cmp_le_i32_e32 vcc, v131, v19
	v_cndmask_b32_e64 v102, v171, v170, s[40:41]
	v_and_b32_e32 v154, 1, v102
	v_cndmask_b32_e64 v172, 0, 1, vcc
	v_cmp_ge_i32_e32 vcc, v131, v19
	v_or_b32_e32 v131, 0x71, v18
	v_add_u32_e32 v140, v6, v15
	v_cndmask_b32_e64 v173, 0, 1, vcc
	v_cmp_le_i32_e32 vcc, v174, v19
	v_cndmask_b32_e64 v102, v173, v172, s[40:41]
	v_and_b32_e32 v155, 1, v102
	v_cndmask_b32_e64 v175, 0, 1, vcc
	v_cmp_ge_i32_e32 vcc, v174, v19
	v_lshlrev_b32_e32 v192, 1, v1
	v_add_u32_e32 v145, v10, v36
	v_cndmask_b32_e64 v176, 0, 1, vcc
	v_cmp_le_i32_e32 vcc, v131, v19
	v_cndmask_b32_e64 v102, v176, v175, s[40:41]
	v_and_b32_e32 v157, 1, v102
	v_cndmask_b32_e64 v177, 0, 1, vcc
	v_cmp_ge_i32_e32 vcc, v131, v19
	v_or_b32_e32 v131, 0x72, v18
	v_add_u32_e32 v146, v10, v4
	v_cndmask_b32_e64 v178, 0, 1, vcc
; #define LAS __attribute__((address_space(3)))
; #define MFMA32(a, b, c) __builtin_amdgcn_mfma_f32_32x32x16_bf16((a), (b), (c), 0, 0, 0)
; __device__ __forceinline__ int crow(int r, int hi) { return (r & 3) + 8 * (r >> 2) + 4 * hi; }
; __device__ __forceinline__ void ssd_item(CP& P, int L, int sq, int hd, int dir, LAS unsigned char* lds) {
;     ...
;     f32x16 st;
; #pragma unroll
;     for (int i = 0; i < 16; ++i) st[i] = 0.f;
;     for (int i = tid; i < 64 * SP / 4; i += 512) ((LAS unsigned*)(lds + S_PV))[i] = 0u;
;     const int crow_ = tid >> 4, cch = tid & 15;
;     const int xrow_ = tid >> 3, xch = tid & 7;
;     const int lb = wid >> 1, pb = wid & 1, nb = wid >> 1;
;     const int trq = (lane & 15) >> 2, trb = ((lane >> 4) & 1) * 32 + (lane & 3) * 8;
;     const int xdo = S_XD + (8 * hi + trq) * SXP + 64 * pb + trb;
;     const int bdo = S_BD + (8 * hi + trq) * SP + 64 * nb + trb;
;     u32x4 cv[4], bv[4], xv[2]; float r0 = 0.f, r1 = 0.f;
;     ...
;     SSD_LOAD(sstart + (dir ? nc - 1 : 0) * 128);
;     ...
;             for (int sb = 0; sb < 4; ++sb) if (sb >= sb0 && sb < sb1) {
;                 f32x16 cb;
; #pragma unroll
;                 for (int i = 0; i < 16; ++i) cb[i] = 0.f;
; #pragma unroll
;                 for (int ks = 0; ks < 8; ++ks) { const bf16x8 av = *(const LAS bf16x8*)(lds + S_BM + (32 * sb + r) * SP + (16 * ks + 8 * hi) * 2);
;                     const bf16x8 bv2 = *(const LAS bf16x8*)(lds + S_CM + lrow * SP + (16 * ks + 8 * hi) * 2); cb = MFMA32(av, bv2, cb); }
; #pragma unroll
;                 for (int i = 0; i < 16; ++i) { const int sr = 32 * sb + crow(i, hi); const bool ok = dir ? (sr >= lrow) : (sr <= lrow); const float gv = cb[i] * __expf(a_l - AS[sr]); cb[i] = ok ? gv : 0.f; }
	v_cmp_le_i32_e32 vcc, v131, v19
	v_cndmask_b32_e64 v102, v178, v177, s[40:41]
	v_and_b32_e32 v158, 1, v102
	v_cndmask_b32_e64 v179, 0, 1, vcc
	v_cmp_ge_i32_e32 vcc, v131, v19
	v_or_b32_e32 v131, 0x73, v18
	v_add_u32_e32 v147, v11, v5
	v_cndmask_b32_e64 v180, 0, 1, vcc
	v_cmp_le_i32_e32 vcc, v131, v19
	v_cndmask_b32_e64 v102, v180, v179, s[40:41]
	v_and_b32_e32 v159, 1, v102
	v_cndmask_b32_e64 v181, 0, 1, vcc
	v_cmp_ge_i32_e32 vcc, v131, v19
	v_or_b32_e32 v131, 0x79, v18
	v_add_u32_e32 v148, v12, v3
	v_cndmask_b32_e64 v182, 0, 1, vcc
	v_cmp_le_i32_e32 vcc, v183, v19
	v_cndmask_b32_e64 v102, v182, v181, s[40:41]
	v_and_b32_e32 v160, 1, v102
	v_cndmask_b32_e64 v184, 0, 1, vcc
	v_cmp_ge_i32_e32 vcc, v183, v19
	v_add_u32_e32 v149, v13, v3
	v_add_u32_e32 v151, v16, v5
	v_cndmask_b32_e64 v185, 0, 1, vcc
	v_cmp_le_i32_e32 vcc, v131, v19
	v_cndmask_b32_e64 v102, v185, v184, s[40:41]
	v_and_b32_e32 v161, 1, v102
	v_cndmask_b32_e64 v186, 0, 1, vcc
	v_cmp_ge_i32_e32 vcc, v131, v19
	v_or_b32_e32 v131, 0x7a, v18
	v_add_u32_e32 v152, v7, v5
	v_cndmask_b32_e64 v187, 0, 1, vcc
	v_cmp_le_i32_e32 vcc, v131, v19
	v_cndmask_b32_e64 v102, v187, v186, s[40:41]
	v_and_b32_e32 v162, 1, v102
	v_cndmask_b32_e64 v188, 0, 1, vcc
	v_cmp_ge_i32_e32 vcc, v131, v19
	v_or_b32_e32 v131, 0x7b, v18
	v_or_b32_e32 v18, s20, v18
	v_cndmask_b32_e64 v189, 0, 1, vcc
	v_cmp_le_i32_e32 vcc, v131, v19
	v_cndmask_b32_e64 v102, v189, v188, s[40:41]
	v_and_b32_e32 v163, 1, v102
	v_cndmask_b32_e64 v190, 0, 1, vcc
	v_cmp_ge_i32_e32 vcc, v131, v19
	v_lshl_add_u32 v131, v27, 2, s24
	v_cndmask_b32_e64 v27, v38, v37, s[40:41]
	v_and_b32_e32 v27, 1, v27
	v_cmp_eq_u32_e64 s[0:1], 1, v27
	v_cndmask_b32_e64 v19, 0, 1, vcc
	v_cndmask_b32_e64 v37, v142, v141, s[40:41]
	v_writelane_b32 v255, s0, 13
	v_cndmask_b32_e64 v38, v144, v143, s[40:41]
	v_cndmask_b32_e64 v19, v19, v190, s[40:41]
	v_writelane_b32 v255, s1, 14
	v_cmp_eq_u32_e64 s[0:1], 1, v28
	v_and_b32_e32 v37, 1, v37
	v_and_b32_e32 v38, 1, v38
	v_writelane_b32 v255, s0, 15
	v_and_b32_e32 v19, 1, v19
	v_mul_u32_u24_e32 v18, 0x110, v18
	v_writelane_b32 v255, s1, 16
	v_cmp_eq_u32_e64 s[0:1], 1, v29
	v_add_u32_e32 v141, v8, v15
	v_add_u32_e32 v142, v9, v17
	v_writelane_b32 v255, s0, 17
	v_lshlrev_b32_e32 v102, 1, v2
	v_add_u32_e32 v143, v10, v20
	v_add_u32_e32 v144, v10, v21
	v_add_u32_e32 v150, v14, v18
	v_mov_b32_e32 v1, v0
	v_mov_b32_e32 v2, v0
	v_mov_b32_e32 v3, v0
	v_mov_b32_e32 v4, v0
	v_mov_b32_e32 v5, v0
	v_mov_b32_e32 v6, v0
	v_mov_b32_e32 v7, v0
	v_mov_b32_e32 v8, v0
	v_mov_b32_e32 v9, v0
	v_mov_b32_e32 v10, v0
	v_mov_b32_e32 v11, v0
	v_mov_b32_e32 v12, v0
	v_mov_b32_e32 v13, v0
	v_mov_b32_e32 v14, v0
	v_mov_b32_e32 v15, v0
	v_writelane_b32 v255, s1, 18
	v_cmp_eq_u32_e64 s[26:27], 1, v30
	v_cmp_eq_u32_e64 s[28:29], 1, v31
	v_cmp_eq_u32_e64 s[30:31], 1, v32
	v_cmp_eq_u32_e64 s[34:35], 1, v33
	v_cmp_eq_u32_e64 s[36:37], 1, v34
	v_cmp_eq_u32_e64 s[38:39], 1, v35
	v_cmp_eq_u32_e64 s[0:1], 1, v37
	v_cmp_eq_u32_e64 s[54:55], 1, v38
	v_cmp_eq_u32_e64 s[56:57], 1, v39
	v_cmp_eq_u32_e64 s[58:59], 1, v40
	v_cmp_eq_u32_e64 s[60:61], 1, v41
	v_cmp_eq_u32_e64 s[62:63], 1, v42
	v_cmp_eq_u32_e64 s[64:65], 1, v43
	v_cmp_eq_u32_e64 s[66:67], 1, v44
	v_cmp_eq_u32_e64 s[68:69], 1, v45
	v_cmp_eq_u32_e64 s[70:71], 1, v46
	v_cmp_eq_u32_e64 s[72:73], 1, v47
	v_cmp_eq_u32_e64 s[74:75], 1, v103
	v_cmp_eq_u32_e64 s[76:77], 1, v153
	v_cmp_eq_u32_e64 s[78:79], 1, v154
	v_cmp_eq_u32_e64 s[80:81], 1, v155
	v_cmp_eq_u32_e64 s[82:83], 1, v157
	v_cmp_eq_u32_e64 s[84:85], 1, v158
	v_cmp_eq_u32_e64 s[86:87], 1, v159
	v_cmp_eq_u32_e64 s[88:89], 1, v160
	v_cmp_eq_u32_e64 s[90:91], 1, v161
	v_cmp_eq_u32_e64 s[92:93], 1, v162
	v_cmp_eq_u32_e64 s[94:95], 1, v163
	v_cmp_eq_u32_e64 s[96:97], 1, v19
	s_mov_b32 s25, 0x41a00000
	v_readlane_b32 s24, v253, 0
	s_waitcnt vmcnt(0)
	s_branch .LBB0_95

; __device__ __forceinline__ void ssd_item(CP& P, int L, int sq, int hd, int dir, LAS unsigned char* lds) {
;     ...
;         if (wid == 0) {
;             const float q0 = r0 + dtb, q1 = r1 + dtb;
;             const float d0 = q0 > 20.f ? q0 : log1pf(__expf(q0)), d1 = q1 > 20.f ? q1 : log1pf(__expf(q1));
.LBB0_95:
	v_cndmask_b32_e64 v16, 0, 1, s[10:11]
	v_cmp_ne_u32_e64 s[98:99], 1, v16
	s_andn2_b64 vcc, exec, s[10:11]
	s_cbranch_vccnz .LBB0_103
	s_waitcnt vmcnt(5)
	v_add_f32_e32 v16, v104, v106
	v_cmp_nlt_f32_e32 vcc, s25, v16
	s_and_saveexec_b64 s[20:21], vcc
	s_cbranch_execz .LBB0_98
	v_mul_f32_e32 v16, 0x3fb8aa3b, v16
	v_exp_f32_e32 v30, v16
	s_mov_b32 s24, 0x3f2aaaab
	v_add_f32_e32 v18, 1.0, v30
	v_frexp_mant_f32_e32 v20, v18
	v_cvt_f64_f32_e32 v[16:17], v18
	v_frexp_exp_i32_f64_e32 v16, v[16:17]
	v_cmp_gt_f32_e32 vcc, s24, v20
	v_add_f32_e32 v19, -1.0, v18
	v_sub_f32_e32 v21, v19, v18
	v_subbrev_co_u32_e32 v24, vcc, 0, v16, vcc
	v_sub_u32_e32 v16, 0, v24
	v_sub_f32_e32 v19, v30, v19
	v_add_f32_e32 v21, 1.0, v21
	v_ldexp_f32 v17, v18, v16
	v_add_f32_e32 v19, v19, v21
	v_add_f32_e32 v18, -1.0, v17
	v_add_f32_e32 v20, 1.0, v17
	v_ldexp_f32 v16, v19, v16
	v_add_f32_e32 v19, 1.0, v18
	v_add_f32_e32 v21, -1.0, v20
	v_sub_f32_e32 v19, v17, v19
	v_sub_f32_e32 v17, v17, v21
	v_add_f32_e32 v19, v16, v19
	v_add_f32_e32 v16, v16, v17
	v_add_f32_e32 v25, v20, v16
	v_rcp_f32_e32 v27, v25
	v_sub_f32_e32 v17, v25, v20
	v_sub_f32_e32 v26, v16, v17
	v_add_f32_e32 v17, v18, v19
	v_mul_f32_e32 v29, v17, v27
	v_sub_f32_e32 v16, v17, v18
	v_mul_f32_e32 v18, v25, v29
	v_fma_f32 v20, v29, v25, -v18
	v_fmac_f32_e32 v20, v29, v26
	v_sub_f32_e32 v28, v19, v16
	v_add_f32_e32 v16, v18, v20
	v_sub_f32_e32 v19, v17, v16
	v_pk_add_f32 v[22:23], v[16:17], v[18:19] neg_lo:[0,1] neg_hi:[0,1]
	v_mov_b32_e32 v21, v16
	v_pk_add_f32 v[16:17], v[22:23], v[20:21] neg_lo:[0,1] neg_hi:[0,1]
	s_mov_b32 s24, 0x3f317218
	v_add_f32_e32 v17, v28, v17
	v_add_f32_e32 v16, v16, v17
	v_add_f32_e32 v17, v19, v16
	v_mul_f32_e32 v28, v27, v17
	v_mul_f32_e32 v18, v25, v28
	v_fma_f32 v20, v28, v25, -v18
	v_fmac_f32_e32 v20, v28, v26
	v_sub_f32_e32 v19, v19, v17
	v_add_f32_e32 v25, v16, v19
	v_add_f32_e32 v16, v18, v20
	v_sub_f32_e32 v19, v17, v16
	v_pk_add_f32 v[22:23], v[16:17], v[18:19] neg_lo:[0,1] neg_hi:[0,1]
	v_mov_b32_e32 v21, v16
	v_pk_add_f32 v[16:17], v[22:23], v[20:21] neg_lo:[0,1] neg_hi:[0,1]
	s_nop 0
	v_add_f32_e32 v17, v25, v17
	v_add_f32_e32 v16, v16, v17
	v_add_f32_e32 v17, v29, v28
	v_add_f32_e32 v16, v19, v16
	v_sub_f32_e32 v18, v17, v29
	v_mul_f32_e32 v16, v27, v16
	v_sub_f32_e32 v18, v28, v18
	v_add_f32_e32 v18, v18, v16
	v_add_f32_e32 v20, v17, v18
	v_mul_f32_e32 v21, v20, v20
	v_fmamk_f32 v16, v21, 0x3e9b6dac, v199
	v_fmaak_f32 v197, v21, v16, 0x3f2aaada
	v_cvt_f32_i32_e32 v16, v24
	v_sub_f32_e32 v17, v20, v17
	v_sub_f32_e32 v17, v18, v17
	v_ldexp_f32 v22, v17, 1
	v_mul_f32_e32 v17, v20, v21
	v_ldexp_f32 v19, v20, 1
	v_pk_mul_f32 v[20:21], v[16:17], v[196:197]
	s_nop 0
	v_fma_f32 v18, v16, s24, -v20
	v_fmac_f32_e32 v18, 0xb102e308, v16
	v_pk_add_f32 v[16:17], v[20:21], v[18:19]
	s_mov_b32 s24, 0x7f800000
	v_sub_f32_e32 v19, v17, v19
	v_sub_f32_e32 v19, v21, v19
	v_add_f32_e32 v23, v22, v19
	v_mov_b32_e32 v22, v20
	v_pk_add_f32 v[20:21], v[16:17], v[20:21] neg_lo:[0,1] neg_hi:[0,1]
	v_pk_add_f32 v[24:25], v[16:17], v[22:23]
	v_mov_b32_e32 v19, v16
	v_mov_b32_e32 v21, v25
	v_pk_add_f32 v[26:27], v[18:19], v[20:21] neg_lo:[0,1] neg_hi:[0,1]
	v_pk_add_f32 v[18:19], v[18:19], v[20:21]
	v_mov_b32_e32 v22, v23
	v_pk_add_f32 v[20:21], v[18:19], v[16:17] op_sel:[1,0] op_sel_hi:[0,1] neg_lo:[0,1] neg_hi:[0,1]
	v_pk_add_f32 v[28:29], v[24:25], v[20:21] op_sel_hi:[1,0] neg_lo:[0,1] neg_hi:[0,1]
	v_mov_b32_e32 v24, v25
	v_mov_b32_e32 v25, v19
	v_pk_mov_b32 v[20:21], v[16:17], v[20:21] op_sel:[1,0]
	v_mov_b32_e32 v23, v16
	v_pk_add_f32 v[20:21], v[24:25], v[20:21] neg_lo:[0,1] neg_hi:[0,1]
	v_mov_b32_e32 v28, v26
	v_pk_add_f32 v[16:17], v[22:23], v[20:21] neg_lo:[0,1] neg_hi:[0,1]
	v_mov_b32_e32 v27, v19
	v_pk_add_f32 v[20:21], v[28:29], v[16:17]
	v_cmp_neq_f32_e32 vcc, s24, v30
	v_pk_add_f32 v[22:23], v[20:21], v[20:21] op_sel:[0,1] op_sel_hi:[1,0]
	s_mov_b32 s24, 0x33800000
	v_pk_add_f32 v[18:19], v[18:19], v[22:23] op_sel:[1,0] op_sel_hi:[0,1]
	v_mov_b32_e32 v21, v18
	v_pk_add_f32 v[24:25], v[20:21], v[26:27] neg_lo:[0,1] neg_hi:[0,1]
	v_mov_b32_e32 v17, v22
	v_sub_f32_e32 v19, v20, v24
	v_pk_add_f32 v[16:17], v[16:17], v[24:25] neg_lo:[0,1] neg_hi:[0,1]
	v_sub_f32_e32 v19, v26, v19
	v_add_f32_e32 v16, v16, v19
	v_add_f32_e32 v16, v16, v17
	v_add_f32_e32 v16, v18, v16
	v_cndmask_b32_e32 v16, v230, v16, vcc
	v_cmp_ngt_f32_e32 vcc, -1.0, v30
	s_nop 1
	v_cndmask_b32_e32 v16, v237, v16, vcc
	v_cmp_neq_f32_e32 vcc, -1.0, v30
	s_nop 1
	v_cndmask_b32_e32 v16, v238, v16, vcc
	v_cmp_lt_f32_e64 vcc, |v30|, s24
	v_readlane_b32 s24, v253, 0
	s_nop 0
	v_cndmask_b32_e32 v16, v16, v30, vcc
; __device__ __forceinline__ void ssd_item(CP& P, int L, int sq, int hd, int dir, LAS unsigned char* lds) {
;     ...
;         if (wid == 0) {
;             const float q0 = r0 + dtb, q1 = r1 + dtb;
;             const float d0 = q0 > 20.f ? q0 : log1pf(__expf(q0)), d1 = q1 > 20.f ? q1 : log1pf(__expf(q1));
.LBB0_98:
	s_or_b64 exec, exec, s[20:21]
	s_waitcnt vmcnt(4)
	v_add_f32_e32 v17, v104, v107
	v_cmp_nlt_f32_e32 vcc, s25, v17
	s_and_saveexec_b64 s[20:21], vcc
	s_cbranch_execz .LBB0_100
	v_mul_f32_e32 v17, 0x3fb8aa3b, v17
	v_exp_f32_e32 v17, v17
	s_mov_b32 s24, 0x3f2aaaab
	v_add_f32_e32 v20, 1.0, v17
	v_frexp_mant_f32_e32 v22, v20
	v_cvt_f64_f32_e32 v[18:19], v20
	v_frexp_exp_i32_f64_e32 v18, v[18:19]
	v_cmp_gt_f32_e32 vcc, s24, v22
	v_add_f32_e32 v21, -1.0, v20
	v_sub_f32_e32 v23, v21, v20
	v_subbrev_co_u32_e32 v26, vcc, 0, v18, vcc
	v_sub_u32_e32 v18, 0, v26
	v_sub_f32_e32 v21, v17, v21
	v_add_f32_e32 v23, 1.0, v23
	v_ldexp_f32 v19, v20, v18
	v_add_f32_e32 v21, v21, v23
	v_add_f32_e32 v20, -1.0, v19
	v_add_f32_e32 v22, 1.0, v19
	v_ldexp_f32 v18, v21, v18
	v_add_f32_e32 v21, 1.0, v20
	v_add_f32_e32 v23, -1.0, v22
	v_sub_f32_e32 v21, v19, v21
	v_sub_f32_e32 v19, v19, v23
	v_add_f32_e32 v21, v18, v21
	v_add_f32_e32 v18, v18, v19
	v_add_f32_e32 v27, v22, v18
	v_rcp_f32_e32 v29, v27
	v_sub_f32_e32 v19, v27, v22
	v_sub_f32_e32 v28, v18, v19
	v_add_f32_e32 v19, v20, v21
	v_mul_f32_e32 v31, v19, v29
	v_sub_f32_e32 v18, v19, v20
	v_mul_f32_e32 v20, v27, v31
	v_fma_f32 v22, v31, v27, -v20
	v_fmac_f32_e32 v22, v31, v28
	v_sub_f32_e32 v30, v21, v18
	v_add_f32_e32 v18, v20, v22
	v_sub_f32_e32 v21, v19, v18
	v_pk_add_f32 v[24:25], v[18:19], v[20:21] neg_lo:[0,1] neg_hi:[0,1]
	v_mov_b32_e32 v23, v18
	v_pk_add_f32 v[18:19], v[24:25], v[22:23] neg_lo:[0,1] neg_hi:[0,1]
	s_mov_b32 s24, 0x3f317218
	v_add_f32_e32 v19, v30, v19
	v_add_f32_e32 v18, v18, v19
	v_add_f32_e32 v19, v21, v18
	v_mul_f32_e32 v30, v29, v19
	v_mul_f32_e32 v20, v27, v30
	v_fma_f32 v22, v30, v27, -v20
	v_fmac_f32_e32 v22, v30, v28
	v_sub_f32_e32 v21, v21, v19
	v_add_f32_e32 v27, v18, v21
	v_add_f32_e32 v18, v20, v22
	v_sub_f32_e32 v21, v19, v18
	v_pk_add_f32 v[24:25], v[18:19], v[20:21] neg_lo:[0,1] neg_hi:[0,1]
	v_mov_b32_e32 v23, v18
	v_pk_add_f32 v[18:19], v[24:25], v[22:23] neg_lo:[0,1] neg_hi:[0,1]
	s_nop 0
	v_add_f32_e32 v19, v27, v19
	v_add_f32_e32 v18, v18, v19
	v_add_f32_e32 v19, v31, v30
	v_add_f32_e32 v18, v21, v18
	v_sub_f32_e32 v20, v19, v31
	v_mul_f32_e32 v18, v29, v18
	v_sub_f32_e32 v20, v30, v20
	v_add_f32_e32 v20, v20, v18
	v_add_f32_e32 v22, v19, v20
	v_mul_f32_e32 v23, v22, v22
	v_fmamk_f32 v18, v23, 0x3e9b6dac, v199
	v_fmaak_f32 v197, v23, v18, 0x3f2aaada
	v_cvt_f32_i32_e32 v18, v26
	v_sub_f32_e32 v19, v22, v19
	v_sub_f32_e32 v19, v20, v19
	v_ldexp_f32 v24, v19, 1
	v_mul_f32_e32 v19, v22, v23
	v_ldexp_f32 v21, v22, 1
	v_pk_mul_f32 v[22:23], v[18:19], v[196:197]
	s_nop 0
	v_fma_f32 v20, v18, s24, -v22
	v_fmac_f32_e32 v20, 0xb102e308, v18
	v_pk_add_f32 v[18:19], v[22:23], v[20:21]
	s_mov_b32 s24, 0x7f800000
	v_sub_f32_e32 v21, v19, v21
	v_sub_f32_e32 v21, v23, v21
	v_add_f32_e32 v25, v24, v21
	v_mov_b32_e32 v24, v22
	v_pk_add_f32 v[22:23], v[18:19], v[22:23] neg_lo:[0,1] neg_hi:[0,1]
	v_pk_add_f32 v[26:27], v[18:19], v[24:25]
	v_mov_b32_e32 v21, v18
	v_mov_b32_e32 v23, v27
	v_pk_add_f32 v[28:29], v[20:21], v[22:23] neg_lo:[0,1] neg_hi:[0,1]
	v_pk_add_f32 v[20:21], v[20:21], v[22:23]
	v_mov_b32_e32 v24, v25
	v_pk_add_f32 v[22:23], v[20:21], v[18:19] op_sel:[1,0] op_sel_hi:[0,1] neg_lo:[0,1] neg_hi:[0,1]
	v_pk_add_f32 v[30:31], v[26:27], v[22:23] op_sel_hi:[1,0] neg_lo:[0,1] neg_hi:[0,1]
	v_mov_b32_e32 v26, v27
	v_mov_b32_e32 v27, v21
	v_pk_mov_b32 v[22:23], v[18:19], v[22:23] op_sel:[1,0]
	v_mov_b32_e32 v25, v18
	v_pk_add_f32 v[22:23], v[26:27], v[22:23] neg_lo:[0,1] neg_hi:[0,1]
	v_mov_b32_e32 v30, v28
	v_pk_add_f32 v[18:19], v[24:25], v[22:23] neg_lo:[0,1] neg_hi:[0,1]
	v_mov_b32_e32 v29, v21
	v_pk_add_f32 v[22:23], v[30:31], v[18:19]
	v_cmp_neq_f32_e32 vcc, s24, v17
	v_pk_add_f32 v[24:25], v[22:23], v[22:23] op_sel:[0,1] op_sel_hi:[1,0]
	s_mov_b32 s24, 0x33800000
	v_pk_add_f32 v[20:21], v[20:21], v[24:25] op_sel:[1,0] op_sel_hi:[0,1]
	v_mov_b32_e32 v23, v20
	v_pk_add_f32 v[26:27], v[22:23], v[28:29] neg_lo:[0,1] neg_hi:[0,1]
	v_mov_b32_e32 v19, v24
	v_sub_f32_e32 v21, v22, v26
	v_pk_add_f32 v[18:19], v[18:19], v[26:27] neg_lo:[0,1] neg_hi:[0,1]
	v_sub_f32_e32 v21, v28, v21
	v_add_f32_e32 v18, v18, v21
	v_add_f32_e32 v18, v18, v19
	v_add_f32_e32 v18, v20, v18
	v_cndmask_b32_e32 v18, v230, v18, vcc
	v_cmp_ngt_f32_e32 vcc, -1.0, v17
	s_nop 1
	v_cndmask_b32_e32 v18, v237, v18, vcc
	v_cmp_neq_f32_e32 vcc, -1.0, v17
	s_nop 1
	v_cndmask_b32_e32 v18, v238, v18, vcc
	v_cmp_lt_f32_e64 vcc, |v17|, s24
	v_readlane_b32 s24, v253, 0
	s_nop 0
	v_cndmask_b32_e32 v17, v18, v17, vcc

; #define LAS __attribute__((address_space(3)))
; __device__ __forceinline__ unsigned cvtpk(float lo, float hi) { f32x2 v = {lo, hi}; bf16x2_t b = __builtin_convertvector(v, bf16x2_t); return __builtin_bit_cast(unsigned, b); }
; __device__ __forceinline__ void ssd_item(CP& P, int L, int sq, int hd, int dir, LAS unsigned char* lds) {
;     ...
;         __syncthreads();
;         { const float aend = AS[128];
; #pragma unroll
;           for (int i = 0; i < 4; ++i) { const int row = crow_ + 32 * i; const float dec = __expf(aend - AS[row]);
;               *(LAS u32x4*)(lds + S_CM + row * SP + cch * 16) = cv[i]; *(LAS u32x4*)(lds + S_BM + row * SP + cch * 16) = bv[i];
;               float f[8]; unpack8(bv[i], f); u32x4 w; w.x = cvtpk(f[0] * dec, f[1] * dec); w.y = cvtpk(f[2] * dec, f[3] * dec); w.z = cvtpk(f[4] * dec, f[5] * dec); w.w = cvtpk(f[6] * dec, f[7] * dec);
;               *(LAS u32x4*)(lds + S_BD + row * SP + cch * 16) = w; }
; #pragma unroll
;           for (int i = 0; i < 2; ++i) { const int row = xrow_ + 64 * i; const float dtv = DTV[row]; float f[8]; unpack8(xv[i], f);
;               u32x4 w; w.x = cvtpk(f[0] * dtv, f[1] * dtv); w.y = cvtpk(f[2] * dtv, f[3] * dtv); w.z = cvtpk(f[4] * dtv, f[5] * dtv); w.w = cvtpk(f[6] * dtv, f[7] * dtv);
;               *(LAS u32x4*)(lds + S_XD + row * SXP + xch * 16) = w; } }
.LBB0_103:
	v_mov_b32_e32 v16, s24
	s_waitcnt lgkmcnt(0)
	s_barrier
	ds_read_b32 v24, v16
	ds_read_b32 v16, v117
	s_waitcnt vmcnt(12)
	v_and_b32_e32 v17, 0xffff0000, v52
	v_lshlrev_b32_e32 v18, 16, v53
	v_and_b32_e32 v19, 0xffff0000, v53
	v_lshlrev_b32_e32 v22, 16, v55
	s_waitcnt lgkmcnt(0)
	v_sub_f32_e32 v16, v24, v16
	v_mul_f32_e32 v16, 0x3fb8aa3b, v16
	v_exp_f32_e32 v20, v16
	v_lshlrev_b32_e32 v16, 16, v52
	v_and_b32_e32 v23, 0xffff0000, v55
	ds_write_b128 v140, v[48:51]
	ds_write_b128 v140, v[52:55] offset:34816
	v_pk_mul_f32 v[16:17], v[20:21], v[16:17] op_sel_hi:[0,1]
	v_pk_mul_f32 v[18:19], v[20:21], v[18:19] op_sel_hi:[0,1]
	v_cvt_pk_bf16_f32 v16, v16, v17
	v_cvt_pk_bf16_f32 v17, v18, v19
	v_lshlrev_b32_e32 v18, 16, v54
	v_and_b32_e32 v19, 0xffff0000, v54
	v_pk_mul_f32 v[18:19], v[20:21], v[18:19] op_sel_hi:[0,1]
	v_pk_mul_f32 v[20:21], v[20:21], v[22:23] op_sel_hi:[0,1]
	v_cvt_pk_bf16_f32 v18, v18, v19
	v_cvt_pk_bf16_f32 v19, v20, v21
	ds_write_b128 v141, v[16:19]
	ds_read_b32 v16, v118
	s_waitcnt vmcnt(10)
	v_and_b32_e32 v17, 0xffff0000, v60
	v_lshlrev_b32_e32 v18, 16, v61
	v_and_b32_e32 v19, 0xffff0000, v61
	v_lshlrev_b32_e32 v22, 16, v63
	s_waitcnt lgkmcnt(0)
	v_sub_f32_e32 v16, v24, v16
	v_mul_f32_e32 v16, 0x3fb8aa3b, v16
	v_exp_f32_e32 v20, v16
	v_lshlrev_b32_e32 v16, 16, v60
	v_and_b32_e32 v23, 0xffff0000, v63
	ds_write_b128 v140, v[56:59] offset:8704
	ds_write_b128 v140, v[60:63] offset:43520
	v_pk_mul_f32 v[16:17], v[20:21], v[16:17] op_sel_hi:[0,1]
	v_pk_mul_f32 v[18:19], v[20:21], v[18:19] op_sel_hi:[0,1]
	v_cvt_pk_bf16_f32 v16, v16, v17
	v_cvt_pk_bf16_f32 v17, v18, v19
	v_lshlrev_b32_e32 v18, 16, v62
	v_and_b32_e32 v19, 0xffff0000, v62
	v_pk_mul_f32 v[18:19], v[20:21], v[18:19] op_sel_hi:[0,1]
	v_pk_mul_f32 v[20:21], v[20:21], v[22:23] op_sel_hi:[0,1]
	v_cvt_pk_bf16_f32 v18, v18, v19
	v_cvt_pk_bf16_f32 v19, v20, v21
	ds_write_b128 v141, v[16:19] offset:8704
	ds_read_b32 v16, v119
	s_waitcnt vmcnt(8)
	v_and_b32_e32 v17, 0xffff0000, v68
	v_lshlrev_b32_e32 v18, 16, v69
	v_and_b32_e32 v19, 0xffff0000, v69
	v_lshlrev_b32_e32 v22, 16, v71
	s_waitcnt lgkmcnt(0)
	v_sub_f32_e32 v16, v24, v16
	v_mul_f32_e32 v16, 0x3fb8aa3b, v16
	v_exp_f32_e32 v20, v16
	v_lshlrev_b32_e32 v16, 16, v68
	v_and_b32_e32 v23, 0xffff0000, v71
	ds_write_b128 v140, v[64:67] offset:17408
	ds_write_b128 v140, v[68:71] offset:52224
	v_pk_mul_f32 v[16:17], v[20:21], v[16:17] op_sel_hi:[0,1]
	v_pk_mul_f32 v[18:19], v[20:21], v[18:19] op_sel_hi:[0,1]
	v_cvt_pk_bf16_f32 v16, v16, v17
	v_cvt_pk_bf16_f32 v17, v18, v19
	v_lshlrev_b32_e32 v18, 16, v70
	v_and_b32_e32 v19, 0xffff0000, v70
	v_pk_mul_f32 v[18:19], v[20:21], v[18:19] op_sel_hi:[0,1]
	v_pk_mul_f32 v[20:21], v[20:21], v[22:23] op_sel_hi:[0,1]
	v_cvt_pk_bf16_f32 v18, v18, v19
	v_cvt_pk_bf16_f32 v19, v20, v21
	ds_write_b128 v141, v[16:19] offset:17408
	ds_read_b32 v16, v120
	s_waitcnt vmcnt(6)
	v_and_b32_e32 v17, 0xffff0000, v76
	v_lshlrev_b32_e32 v18, 16, v77
	v_and_b32_e32 v19, 0xffff0000, v77
	v_lshlrev_b32_e32 v22, 16, v79
	s_waitcnt lgkmcnt(0)
	v_sub_f32_e32 v16, v24, v16
	v_mul_f32_e32 v16, 0x3fb8aa3b, v16
	v_exp_f32_e32 v20, v16
	v_lshlrev_b32_e32 v16, 16, v76
	v_and_b32_e32 v23, 0xffff0000, v79
	ds_write_b128 v140, v[72:75] offset:26112
	ds_write_b128 v140, v[76:79] offset:60928
	v_pk_mul_f32 v[16:17], v[20:21], v[16:17] op_sel_hi:[0,1]
	v_pk_mul_f32 v[18:19], v[20:21], v[18:19] op_sel_hi:[0,1]
	v_cvt_pk_bf16_f32 v16, v16, v17
	v_cvt_pk_bf16_f32 v17, v18, v19
	v_lshlrev_b32_e32 v18, 16, v78
	v_and_b32_e32 v19, 0xffff0000, v78
	v_pk_mul_f32 v[18:19], v[20:21], v[18:19] op_sel_hi:[0,1]
	v_pk_mul_f32 v[20:21], v[20:21], v[22:23] op_sel_hi:[0,1]
	v_cvt_pk_bf16_f32 v18, v18, v19
	v_cvt_pk_bf16_f32 v19, v20, v21
	ds_write_b128 v141, v[16:19] offset:26112
	ds_read_b32 v20, v121
	s_waitcnt vmcnt(5)
	v_lshlrev_b32_e32 v16, 16, v80
	v_and_b32_e32 v17, 0xffff0000, v80
	v_lshlrev_b32_e32 v18, 16, v81
	v_and_b32_e32 v19, 0xffff0000, v81
	s_waitcnt lgkmcnt(0)
	v_pk_mul_f32 v[16:17], v[20:21], v[16:17] op_sel_hi:[0,1]
	v_pk_mul_f32 v[18:19], v[20:21], v[18:19] op_sel_hi:[0,1]
	v_cvt_pk_bf16_f32 v16, v16, v17
	v_cvt_pk_bf16_f32 v17, v18, v19
	v_lshlrev_b32_e32 v18, 16, v82
	v_and_b32_e32 v19, 0xffff0000, v82
	v_lshlrev_b32_e32 v22, 16, v83
	v_and_b32_e32 v23, 0xffff0000, v83
	v_pk_mul_f32 v[18:19], v[20:21], v[18:19] op_sel_hi:[0,1]
	v_pk_mul_f32 v[20:21], v[20:21], v[22:23] op_sel_hi:[0,1]
	v_cvt_pk_bf16_f32 v18, v18, v19
	v_cvt_pk_bf16_f32 v19, v20, v21
	ds_write_b128 v142, v[16:19]
	ds_read_b32 v20, v122
	s_waitcnt vmcnt(4)
	v_lshlrev_b32_e32 v16, 16, v84
	v_and_b32_e32 v17, 0xffff0000, v84
	v_lshlrev_b32_e32 v18, 16, v85
	v_and_b32_e32 v19, 0xffff0000, v85
	s_waitcnt lgkmcnt(0)
	v_pk_mul_f32 v[16:17], v[20:21], v[16:17] op_sel_hi:[0,1]
	v_pk_mul_f32 v[18:19], v[20:21], v[18:19] op_sel_hi:[0,1]
	v_cvt_pk_bf16_f32 v16, v16, v17
	v_cvt_pk_bf16_f32 v17, v18, v19
	v_lshlrev_b32_e32 v18, 16, v86
	v_and_b32_e32 v19, 0xffff0000, v86
	v_lshlrev_b32_e32 v22, 16, v87
	v_and_b32_e32 v23, 0xffff0000, v87
	v_pk_mul_f32 v[18:19], v[20:21], v[18:19] op_sel_hi:[0,1]
	v_pk_mul_f32 v[20:21], v[20:21], v[22:23] op_sel_hi:[0,1]
	v_cvt_pk_bf16_f32 v18, v18, v19
	v_cvt_pk_bf16_f32 v19, v20, v21
	s_cmp_ge_u32 s23, s2
	ds_write_b128 v142, v[16:19] offset:9216
	s_cbranch_scc1 .LBB0_106
; __device__ __forceinline__ void ssd_item(CP& P, int L, int sq, int hd, int dir, LAS unsigned char* lds) {
;     ...
;         if (ci + 1 < nc) SSD_LOAD(sstart + (dir ? nc - 2 - ci : ci + 1) * 128);
	s_add_i32 vcc_lo, s22, -1
	s_and_b64 s[20:21], s[40:41], exec
	s_cselect_b32 s20, s23, vcc_lo
	s_lshl_b32 s20, s20, 7
	v_readlane_b32 s21, v254, 10
	s_add_i32 s20, s20, s21
	s_mul_i32 vcc_lo, s20, 0xa00
	v_readlane_b32 vcc_hi, v253, 62
	s_mul_hi_i32 s21, s20, 0xa00
	s_add_u32 vcc_lo, vcc_hi, vcc_lo
	v_readlane_b32 vcc_hi, v253, 63
	s_addc_u32 vcc_hi, vcc_hi, s21
	v_mov_b32_e32 v103, v193
	v_lshl_add_u64 v[16:17], vcc, 0, v[88:89]
	v_lshl_add_u64 v[16:17], v[16:17], 0, s[6:7]
	v_lshl_add_u64 v[16:17], v[16:17], 0, v[192:193]
	global_load_dwordx4 v[48:51], v[16:17], off offset:2048
	global_load_dwordx4 v[52:55], v[16:17], off offset:1536
	v_lshl_add_u64 v[16:17], vcc, 0, v[90:91]
	v_lshl_add_u64 v[16:17], v[16:17], 0, s[6:7]
	v_lshl_add_u64 v[16:17], v[16:17], 0, v[192:193]
	global_load_dwordx4 v[56:59], v[16:17], off offset:2048
	global_load_dwordx4 v[60:63], v[16:17], off offset:1536
	v_lshl_add_u64 v[16:17], vcc, 0, v[92:93]
	v_lshl_add_u64 v[16:17], v[16:17], 0, s[6:7]
	v_lshl_add_u64 v[16:17], v[16:17], 0, v[192:193]
	global_load_dwordx4 v[64:67], v[16:17], off offset:2048
	global_load_dwordx4 v[68:71], v[16:17], off offset:1536
	v_lshl_add_u64 v[16:17], vcc, 0, v[94:95]
	v_lshl_add_u64 v[16:17], v[16:17], 0, s[6:7]
	s_add_u32 vcc_lo, vcc_lo, s8
	v_lshl_add_u64 v[16:17], v[16:17], 0, v[192:193]
	s_addc_u32 vcc_hi, vcc_hi, s9
	global_load_dwordx4 v[72:75], v[16:17], off offset:2048
	global_load_dwordx4 v[76:79], v[16:17], off offset:1536
	v_lshl_add_u64 v[16:17], vcc, 0, v[102:103]
	v_lshl_add_u64 v[18:19], v[16:17], 0, v[96:97]
	v_lshl_add_u64 v[16:17], v[16:17], 0, v[98:99]
	global_load_dwordx4 v[80:83], v[18:19], off
	global_load_dwordx4 v[84:87], v[16:17], off
	s_and_b64 vcc, exec, s[98:99]
	s_cbranch_vccnz .LBB0_106
	v_or_b32_e32 v16, s20, v105
	v_ashrrev_i32_e32 v17, 31, v16
	v_lshlrev_b64 v[18:19], 7, v[16:17]
	v_or_b32_e32 v16, 64, v16
	v_readlane_b32 s20, v254, 11
	v_ashrrev_i32_e32 v17, 31, v16
	v_readlane_b32 s21, v254, 12
	v_lshlrev_b64 v[16:17], 7, v[16:17]
	s_nop 0
	v_lshl_add_u64 v[18:19], s[20:21], 0, v[18:19]
	v_lshl_add_u64 v[16:17], s[20:21], 0, v[16:17]
	global_load_dword v106, v[18:19], off
	global_load_dword v107, v[16:17], off
